# v3 + first K-loop iteration peeled in all six GEMMs: first MFMA of each accumulator uses inline 0 as C, 128 v_mov zero-inits per tile removed
# speedup vs baseline: 1.0040x; 1.0040x over previous
.LBB0_159:
	s_ashr_i32 s5, s4, 31
	s_lshl_b64 s[10:11], s[4:5], 20
	s_add_u32 s10, s22, s10
	s_addc_u32 s11, s23, s11
	s_and_b64 s[12:13], s[8:9], exec
	s_cselect_b32 s5, s11, s17
	s_cselect_b32 s43, s10, s16
	s_ashr_i32 s7, s6, 31
	s_lshl_b64 s[12:13], s[6:7], 20
	s_add_u32 s12, s24, s12
	s_addc_u32 s13, s25, s13
	s_and_b64 s[18:19], s[8:9], exec
	s_cselect_b32 s7, s13, s15
	s_cselect_b32 s44, s12, s14
	s_add_u32 s45, s14, 0x10000
	s_addc_u32 s46, s15, 0
	s_add_u32 s14, s16, 0x80080
	s_addc_u32 s15, s17, 0
	s_mov_b32 s47, -2
	s_add_u32 s16, s14, 0xfff80080
	s_addc_u32 s17, s15, -1
	s_add_i32 s48, 0, 0x10000
	s_cmp_eq_u32 s47, 28
	s_cselect_b32 s19, s5, s17
	s_cselect_b32 s18, s43, s16
	s_cselect_b32 s17, s7, s46
	s_cselect_b32 s16, s44, s45
	s_add_i32 s50, 0, 0x14000
	v_add_u32_e32 v168, s48, v158
	v_add_u32_e32 v184, s50, v158
	ds_read_b128 v[154:157], v168
	ds_read_b128 v[160:163], v168 offset:1024
	ds_read_b128 v[164:167], v168 offset:2048
	ds_read_b128 v[168:171], v168 offset:3072
	ds_read_b128 v[172:175], v184
	ds_read_b128 v[176:179], v184 offset:1024
	ds_read_b128 v[180:183], v184 offset:2048
	ds_read_b128 v[184:187], v184 offset:3072
	v_lshl_add_u64 v[204:205], s[14:15], 0, v[150:151]
	s_add_i32 m0, s28, 0xc000
	ds_read_b128 v[188:191], v159
	ds_read_b128 v[192:195], v159 offset:1024
	ds_read_b128 v[196:199], v159 offset:2048
	ds_read_b128 v[200:203], v159 offset:3072
	ds_read_b128 v[214:217], v159 offset:4096
	ds_read_b128 v[218:221], v159 offset:5120
	ds_read_b128 v[222:225], v159 offset:6144
	ds_read_b128 v[226:229], v159 offset:7168
	global_load_lds_dwordx4 v[204:205], off
	v_lshl_add_u64 v[204:205], s[14:15], 0, v[152:153]
	s_add_i32 m0, s28, 0xe000
	s_nop 0
	global_load_lds_dwordx4 v[204:205], off
	s_waitcnt vmcnt(8)
	s_waitcnt lgkmcnt(0)
	s_barrier
	s_setprio 1
	s_waitcnt lgkmcnt(0)
	v_mfma_f32_16x16x32_bf16 v[128:131], v[154:157], v[188:191], 0
	v_mfma_f32_16x16x32_bf16 v[120:123], v[164:167], v[188:191], 0
	v_mfma_f32_16x16x32_bf16 v[112:115], v[154:157], v[196:199], 0
	v_mfma_f32_16x16x32_bf16 v[104:107], v[164:167], v[196:199], 0
	v_mfma_f32_16x16x32_bf16 v[96:99], v[154:157], v[214:217], 0
	v_mfma_f32_16x16x32_bf16 v[88:91], v[164:167], v[214:217], 0
	v_mfma_f32_16x16x32_bf16 v[80:83], v[154:157], v[222:225], 0
	v_mfma_f32_16x16x32_bf16 v[72:75], v[164:167], v[222:225], 0
	v_mfma_f32_16x16x32_bf16 v[128:131], v[160:163], v[192:195], v[128:131]
	v_mfma_f32_16x16x32_bf16 v[120:123], v[168:171], v[192:195], v[120:123]
	v_mfma_f32_16x16x32_bf16 v[112:115], v[160:163], v[200:203], v[112:115]
	v_mfma_f32_16x16x32_bf16 v[104:107], v[168:171], v[200:203], v[104:107]
	v_mfma_f32_16x16x32_bf16 v[96:99], v[160:163], v[218:221], v[96:99]
	v_mfma_f32_16x16x32_bf16 v[88:91], v[168:171], v[218:221], v[88:91]
	v_mfma_f32_16x16x32_bf16 v[80:83], v[160:163], v[226:229], v[80:83]
	v_mfma_f32_16x16x32_bf16 v[72:75], v[168:171], v[226:229], v[72:75]
	s_setprio 0
	s_setprio 1
	v_mfma_f32_16x16x32_bf16 v[124:127], v[172:175], v[188:191], 0
	v_mfma_f32_16x16x32_bf16 v[116:119], v[180:183], v[188:191], 0
	v_mfma_f32_16x16x32_bf16 v[108:111], v[172:175], v[196:199], 0
	v_mfma_f32_16x16x32_bf16 v[100:103], v[180:183], v[196:199], 0
	v_mfma_f32_16x16x32_bf16 v[92:95], v[172:175], v[214:217], 0
	v_mfma_f32_16x16x32_bf16 v[84:87], v[180:183], v[214:217], 0
	v_mfma_f32_16x16x32_bf16 v[76:79], v[172:175], v[222:225], 0
	v_mfma_f32_16x16x32_bf16 v[68:71], v[180:183], v[222:225], 0
	v_mfma_f32_16x16x32_bf16 v[124:127], v[176:179], v[192:195], v[124:127]
	v_mfma_f32_16x16x32_bf16 v[116:119], v[184:187], v[192:195], v[116:119]
	v_mfma_f32_16x16x32_bf16 v[108:111], v[176:179], v[200:203], v[108:111]
	v_mfma_f32_16x16x32_bf16 v[100:103], v[184:187], v[200:203], v[100:103]
	v_mfma_f32_16x16x32_bf16 v[92:95], v[176:179], v[218:221], v[92:95]
	v_mfma_f32_16x16x32_bf16 v[84:87], v[184:187], v[218:221], v[84:87]
	v_mfma_f32_16x16x32_bf16 v[76:79], v[176:179], v[226:229], v[76:79]
	v_mfma_f32_16x16x32_bf16 v[68:71], v[184:187], v[226:229], v[68:71]
	s_setprio 0
	s_barrier
	s_add_i32 s48, s48, s27
	v_lshl_add_u64 v[204:205], s[16:17], 0, v[136:137]
	s_mov_b32 m0, s48
	ds_read_b128 v[188:191], v159 offset:16384
	ds_read_b128 v[192:195], v159 offset:17408
	ds_read_b128 v[196:199], v159 offset:18432
	ds_read_b128 v[200:203], v159 offset:19456
	ds_read_b128 v[214:217], v159 offset:20480
	ds_read_b128 v[218:221], v159 offset:21504
	ds_read_b128 v[222:225], v159 offset:22528
	ds_read_b128 v[226:229], v159 offset:23552
	global_load_lds_dwordx4 v[204:205], off
	s_add_i32 m0, s48, 0x2000
	s_add_u32 s48, s16, 0x4000
	v_lshl_add_u64 v[204:205], s[16:17], 0, v[132:133]
	s_addc_u32 s49, s17, 0
	s_add_i32 s50, s50, s27
	global_load_lds_dwordx4 v[204:205], off
	v_lshl_add_u64 v[204:205], s[48:49], 0, v[136:137]
	s_mov_b32 m0, s50
	v_lshl_add_u64 v[206:207], s[18:19], 0, v[134:135]
	global_load_lds_dwordx4 v[204:205], off
	v_lshl_add_u64 v[204:205], s[48:49], 0, v[132:133]
	s_add_i32 m0, s50, 0x2000
	s_nop 0
	global_load_lds_dwordx4 v[204:205], off
	v_lshl_add_u64 v[204:205], s[18:19], 0, v[138:139]
	s_mov_b32 m0, s28
	s_nop 0
	global_load_lds_dwordx4 v[204:205], off
	s_mov_b32 m0, s29
	s_nop 0
	global_load_lds_dwordx4 v[206:207], off
	s_waitcnt vmcnt(8)
	s_waitcnt lgkmcnt(0)
	s_barrier
	s_setprio 1
	s_waitcnt lgkmcnt(0)
	v_mfma_f32_16x16x32_bf16 v[64:67], v[154:157], v[188:191], 0
	v_mfma_f32_16x16x32_bf16 v[56:59], v[164:167], v[188:191], 0
	v_mfma_f32_16x16x32_bf16 v[48:51], v[154:157], v[196:199], 0
	v_mfma_f32_16x16x32_bf16 v[40:43], v[164:167], v[196:199], 0
	v_mfma_f32_16x16x32_bf16 v[32:35], v[154:157], v[214:217], 0
	v_mfma_f32_16x16x32_bf16 v[24:27], v[164:167], v[214:217], 0
	v_mfma_f32_16x16x32_bf16 v[16:19], v[154:157], v[222:225], 0
	v_mfma_f32_16x16x32_bf16 v[8:11], v[164:167], v[222:225], 0
	v_mfma_f32_16x16x32_bf16 v[64:67], v[160:163], v[192:195], v[64:67]
	v_mfma_f32_16x16x32_bf16 v[56:59], v[168:171], v[192:195], v[56:59]
	v_mfma_f32_16x16x32_bf16 v[48:51], v[160:163], v[200:203], v[48:51]
	v_mfma_f32_16x16x32_bf16 v[40:43], v[168:171], v[200:203], v[40:43]
	v_mfma_f32_16x16x32_bf16 v[32:35], v[160:163], v[218:221], v[32:35]
	v_mfma_f32_16x16x32_bf16 v[24:27], v[168:171], v[218:221], v[24:27]
	v_mfma_f32_16x16x32_bf16 v[16:19], v[160:163], v[226:229], v[16:19]
	v_mfma_f32_16x16x32_bf16 v[8:11], v[168:171], v[226:229], v[8:11]
	s_setprio 0
	s_setprio 1
	v_mfma_f32_16x16x32_bf16 v[60:63], v[172:175], v[188:191], 0
	v_mfma_f32_16x16x32_bf16 v[52:55], v[180:183], v[188:191], 0
	v_mfma_f32_16x16x32_bf16 v[44:47], v[172:175], v[196:199], 0
	v_mfma_f32_16x16x32_bf16 v[36:39], v[180:183], v[196:199], 0
	v_mfma_f32_16x16x32_bf16 v[28:31], v[172:175], v[214:217], 0
	v_mfma_f32_16x16x32_bf16 v[20:23], v[180:183], v[214:217], 0
	v_mfma_f32_16x16x32_bf16 v[12:15], v[172:175], v[222:225], 0
	v_mfma_f32_16x16x32_bf16 v[4:7], v[180:183], v[222:225], 0
	v_mfma_f32_16x16x32_bf16 v[60:63], v[176:179], v[192:195], v[60:63]
	v_mfma_f32_16x16x32_bf16 v[52:55], v[184:187], v[192:195], v[52:55]
	v_mfma_f32_16x16x32_bf16 v[44:47], v[176:179], v[200:203], v[44:47]
	v_mfma_f32_16x16x32_bf16 v[36:39], v[184:187], v[200:203], v[36:39]
	v_mfma_f32_16x16x32_bf16 v[28:31], v[176:179], v[218:221], v[28:31]
	v_mfma_f32_16x16x32_bf16 v[20:23], v[184:187], v[218:221], v[20:23]
	v_mfma_f32_16x16x32_bf16 v[12:15], v[176:179], v[226:229], v[12:15]
	v_mfma_f32_16x16x32_bf16 v[4:7], v[184:187], v[226:229], v[4:7]
	s_setprio 0
	s_barrier
	s_add_i32 s48, 0, 0x18000
	s_add_i32 s49, 0, 0x1c000
	v_add_u32_e32 v168, s48, v158
	v_add_u32_e32 v184, s49, v158
	ds_read_b128 v[154:157], v168
	ds_read_b128 v[160:163], v168 offset:1024
	ds_read_b128 v[164:167], v168 offset:2048
	ds_read_b128 v[168:171], v168 offset:3072
	ds_read_b128 v[172:175], v184
	ds_read_b128 v[176:179], v184 offset:1024
	ds_read_b128 v[180:183], v184 offset:2048
	ds_read_b128 v[184:187], v184 offset:3072
	s_add_u32 s18, s18, 0x80000
	s_addc_u32 s19, s19, 0
	s_mov_b32 m0, s30
	v_lshl_add_u64 v[208:209], s[18:19], 0, v[138:139]
	ds_read_b128 v[188:191], v159 offset:32768
	ds_read_b128 v[192:195], v159 offset:33792
	ds_read_b128 v[196:199], v159 offset:34816
	ds_read_b128 v[200:203], v159 offset:35840
	ds_read_b128 v[214:217], v159 offset:36864
	ds_read_b128 v[218:221], v159 offset:37888
	ds_read_b128 v[222:225], v159 offset:38912
	ds_read_b128 v[226:229], v159 offset:39936
	global_load_lds_dwordx4 v[208:209], off
	v_lshl_add_u64 v[208:209], s[18:19], 0, v[134:135]
	s_mov_b32 m0, s31
	s_nop 0
	global_load_lds_dwordx4 v[208:209], off
	s_waitcnt vmcnt(8)
	s_waitcnt lgkmcnt(0)
	s_barrier
	s_setprio 1
	s_waitcnt lgkmcnt(0)
	v_mfma_f32_16x16x32_bf16 v[128:131], v[154:157], v[188:191], v[128:131]
	v_mfma_f32_16x16x32_bf16 v[120:123], v[164:167], v[188:191], v[120:123]
	v_mfma_f32_16x16x32_bf16 v[112:115], v[154:157], v[196:199], v[112:115]
	v_mfma_f32_16x16x32_bf16 v[104:107], v[164:167], v[196:199], v[104:107]
	v_mfma_f32_16x16x32_bf16 v[96:99], v[154:157], v[214:217], v[96:99]
	v_mfma_f32_16x16x32_bf16 v[88:91], v[164:167], v[214:217], v[88:91]
	v_mfma_f32_16x16x32_bf16 v[80:83], v[154:157], v[222:225], v[80:83]
	v_mfma_f32_16x16x32_bf16 v[72:75], v[164:167], v[222:225], v[72:75]
	v_mfma_f32_16x16x32_bf16 v[128:131], v[160:163], v[192:195], v[128:131]
	v_mfma_f32_16x16x32_bf16 v[120:123], v[168:171], v[192:195], v[120:123]
	v_mfma_f32_16x16x32_bf16 v[112:115], v[160:163], v[200:203], v[112:115]
	v_mfma_f32_16x16x32_bf16 v[104:107], v[168:171], v[200:203], v[104:107]
	v_mfma_f32_16x16x32_bf16 v[96:99], v[160:163], v[218:221], v[96:99]
	v_mfma_f32_16x16x32_bf16 v[88:91], v[168:171], v[218:221], v[88:91]
	v_mfma_f32_16x16x32_bf16 v[80:83], v[160:163], v[226:229], v[80:83]
	v_mfma_f32_16x16x32_bf16 v[72:75], v[168:171], v[226:229], v[72:75]
	s_setprio 0
	s_setprio 1
	v_mfma_f32_16x16x32_bf16 v[124:127], v[172:175], v[188:191], v[124:127]
	v_mfma_f32_16x16x32_bf16 v[116:119], v[180:183], v[188:191], v[116:119]
	v_mfma_f32_16x16x32_bf16 v[108:111], v[172:175], v[196:199], v[108:111]
	v_mfma_f32_16x16x32_bf16 v[100:103], v[180:183], v[196:199], v[100:103]
	v_mfma_f32_16x16x32_bf16 v[92:95], v[172:175], v[214:217], v[92:95]
	v_mfma_f32_16x16x32_bf16 v[84:87], v[180:183], v[214:217], v[84:87]
	v_mfma_f32_16x16x32_bf16 v[76:79], v[172:175], v[222:225], v[76:79]
	v_mfma_f32_16x16x32_bf16 v[68:71], v[180:183], v[222:225], v[68:71]
	v_mfma_f32_16x16x32_bf16 v[124:127], v[176:179], v[192:195], v[124:127]
	v_mfma_f32_16x16x32_bf16 v[116:119], v[184:187], v[192:195], v[116:119]
	v_mfma_f32_16x16x32_bf16 v[108:111], v[176:179], v[200:203], v[108:111]
	v_mfma_f32_16x16x32_bf16 v[100:103], v[184:187], v[200:203], v[100:103]
	v_mfma_f32_16x16x32_bf16 v[92:95], v[176:179], v[218:221], v[92:95]
	v_mfma_f32_16x16x32_bf16 v[84:87], v[184:187], v[218:221], v[84:87]
	v_mfma_f32_16x16x32_bf16 v[76:79], v[176:179], v[226:229], v[76:79]
	v_mfma_f32_16x16x32_bf16 v[68:71], v[184:187], v[226:229], v[68:71]
	s_setprio 0
	s_barrier
	s_add_u32 s18, s16, 0x8000
	s_addc_u32 s19, s17, 0
	s_add_i32 s48, s48, s27
	v_lshl_add_u64 v[208:209], s[18:19], 0, v[136:137]
	s_mov_b32 m0, s48
	ds_read_b128 v[188:191], v159 offset:49152
	ds_read_b128 v[192:195], v159 offset:50176
	ds_read_b128 v[196:199], v159 offset:51200
	ds_read_b128 v[200:203], v159 offset:52224
	ds_read_b128 v[214:217], v159 offset:53248
	ds_read_b128 v[218:221], v159 offset:54272
	ds_read_b128 v[222:225], v159 offset:55296
	ds_read_b128 v[226:229], v159 offset:56320
	global_load_lds_dwordx4 v[208:209], off
	s_add_i32 m0, s48, 0x2000
	s_add_u32 s16, s16, 0xc000
	v_lshl_add_u64 v[208:209], s[18:19], 0, v[132:133]
	s_addc_u32 s17, s17, 0
	s_add_i32 s18, s49, s27
	global_load_lds_dwordx4 v[208:209], off
	v_lshl_add_u64 v[208:209], s[16:17], 0, v[136:137]
	s_mov_b32 m0, s18
	v_lshl_add_u64 v[204:205], v[204:205], 0, s[74:75]
	global_load_lds_dwordx4 v[208:209], off
	v_lshl_add_u64 v[208:209], s[16:17], 0, v[132:133]
	s_add_i32 m0, s18, 0x2000
	s_nop 0
	global_load_lds_dwordx4 v[208:209], off
	s_mov_b32 m0, s38
	s_nop 0
	global_load_lds_dwordx4 v[204:205], off
	v_lshl_add_u64 v[204:205], v[206:207], 0, s[74:75]
	s_mov_b32 m0, s39
	s_nop 0
	global_load_lds_dwordx4 v[204:205], off
	s_waitcnt vmcnt(8)
	s_waitcnt lgkmcnt(0)
	s_barrier
	s_setprio 1
	s_waitcnt lgkmcnt(0)
	v_mfma_f32_16x16x32_bf16 v[64:67], v[154:157], v[188:191], v[64:67]
	v_mfma_f32_16x16x32_bf16 v[56:59], v[164:167], v[188:191], v[56:59]
	v_mfma_f32_16x16x32_bf16 v[48:51], v[154:157], v[196:199], v[48:51]
	v_mfma_f32_16x16x32_bf16 v[40:43], v[164:167], v[196:199], v[40:43]
	v_mfma_f32_16x16x32_bf16 v[32:35], v[154:157], v[214:217], v[32:35]
	v_mfma_f32_16x16x32_bf16 v[24:27], v[164:167], v[214:217], v[24:27]
	v_mfma_f32_16x16x32_bf16 v[16:19], v[154:157], v[222:225], v[16:19]
	v_mfma_f32_16x16x32_bf16 v[8:11], v[164:167], v[222:225], v[8:11]
	v_mfma_f32_16x16x32_bf16 v[64:67], v[160:163], v[192:195], v[64:67]
	v_mfma_f32_16x16x32_bf16 v[56:59], v[168:171], v[192:195], v[56:59]
	v_mfma_f32_16x16x32_bf16 v[48:51], v[160:163], v[200:203], v[48:51]
	v_mfma_f32_16x16x32_bf16 v[40:43], v[168:171], v[200:203], v[40:43]
	v_mfma_f32_16x16x32_bf16 v[32:35], v[160:163], v[218:221], v[32:35]
	v_mfma_f32_16x16x32_bf16 v[24:27], v[168:171], v[218:221], v[24:27]
	v_mfma_f32_16x16x32_bf16 v[16:19], v[160:163], v[226:229], v[16:19]
	v_mfma_f32_16x16x32_bf16 v[8:11], v[168:171], v[226:229], v[8:11]
	s_setprio 0
	s_setprio 1
	v_mfma_f32_16x16x32_bf16 v[60:63], v[172:175], v[188:191], v[60:63]
	v_mfma_f32_16x16x32_bf16 v[52:55], v[180:183], v[188:191], v[52:55]
	v_mfma_f32_16x16x32_bf16 v[44:47], v[172:175], v[196:199], v[44:47]
	v_mfma_f32_16x16x32_bf16 v[36:39], v[180:183], v[196:199], v[36:39]
	v_mfma_f32_16x16x32_bf16 v[28:31], v[172:175], v[214:217], v[28:31]
	v_mfma_f32_16x16x32_bf16 v[20:23], v[180:183], v[214:217], v[20:23]
	v_mfma_f32_16x16x32_bf16 v[12:15], v[172:175], v[222:225], v[12:15]
	v_mfma_f32_16x16x32_bf16 v[4:7], v[180:183], v[222:225], v[4:7]
	v_mfma_f32_16x16x32_bf16 v[60:63], v[176:179], v[192:195], v[60:63]
	v_mfma_f32_16x16x32_bf16 v[52:55], v[184:187], v[192:195], v[52:55]
	v_mfma_f32_16x16x32_bf16 v[44:47], v[176:179], v[200:203], v[44:47]
	v_mfma_f32_16x16x32_bf16 v[36:39], v[184:187], v[200:203], v[36:39]
	v_mfma_f32_16x16x32_bf16 v[28:31], v[176:179], v[218:221], v[28:31]
	v_mfma_f32_16x16x32_bf16 v[20:23], v[184:187], v[218:221], v[20:23]
	v_mfma_f32_16x16x32_bf16 v[12:15], v[176:179], v[226:229], v[12:15]
	v_mfma_f32_16x16x32_bf16 v[4:7], v[184:187], v[226:229], v[4:7]
	s_setprio 0
	s_barrier
	s_add_i32 s47, s47, 2
	s_add_u32 s45, s45, 0x10000
	s_addc_u32 s46, s46, 0
	s_add_u32 s14, s14, 0x100
	s_addc_u32 s15, s15, 0
	s_cmp_gt_u32 s47, 29

.LBB0_225:
	s_add_u32 s18, s22, 0xc000
	s_addc_u32 s19, s23, 0
	s_add_u32 s2, s20, 0x10000
	s_addc_u32 s3, s21, 0
	s_mov_b32 s24, -2
	s_add_u32 s14, s18, 0x4000
	s_addc_u32 s15, s19, 0
	s_cmpk_eq_i32 s24, 0x54
	s_cselect_b32 s22, s30, s14
	s_cselect_b32 s23, s31, s15
	s_cselect_b32 s20, s38, s2
	s_cselect_b32 s21, s39, s3
	s_add_u32 s14, s22, 0x8000
	s_addc_u32 s15, s23, 0
	s_add_i32 s25, 0, 0x10000
	s_add_i32 s50, 0, 0x14000
	v_add_u32_e32 v144, s25, v174
	v_add_u32_e32 v160, s50, v174
	ds_read_b128 v[132:135], v144
	ds_read_b128 v[136:139], v144 offset:1024
	ds_read_b128 v[140:143], v144 offset:2048
	ds_read_b128 v[144:147], v144 offset:3072
	ds_read_b128 v[148:151], v160
	ds_read_b128 v[152:155], v160 offset:1024
	ds_read_b128 v[156:159], v160 offset:2048
	ds_read_b128 v[160:163], v160 offset:3072
	v_lshl_add_u64 v[206:207], s[18:19], 0, v[166:167]
	s_add_i32 m0, s65, 0xc000
	ds_read_b128 v[170:173], v182
	ds_read_b128 v[186:189], v182 offset:1024
	ds_read_b128 v[190:193], v182 offset:2048
	ds_read_b128 v[194:197], v182 offset:3072
	ds_read_b128 v[198:201], v182 offset:4096
	ds_read_b128 v[202:205], v182 offset:5120
	ds_read_b128 v[214:217], v182 offset:6144
	ds_read_b128 v[218:221], v182 offset:7168
	global_load_lds_dwordx4 v[206:207], off
	v_lshl_add_u64 v[206:207], s[18:19], 0, v[168:169]
	s_add_i32 m0, s65, 0xe000
	s_nop 0
	global_load_lds_dwordx4 v[206:207], off
	s_waitcnt vmcnt(8)
	s_waitcnt lgkmcnt(0)
	s_barrier
	s_setprio 1
	s_waitcnt lgkmcnt(0)
	v_mfma_f32_16x16x32_bf16 v[128:131], v[132:135], v[170:173], 0
	v_mfma_f32_16x16x32_bf16 v[124:127], v[140:143], v[170:173], 0
	v_mfma_f32_16x16x32_bf16 v[108:111], v[132:135], v[190:193], 0
	v_mfma_f32_16x16x32_bf16 v[116:119], v[140:143], v[190:193], 0
	v_mfma_f32_16x16x32_bf16 v[92:95], v[132:135], v[198:201], 0
	v_mfma_f32_16x16x32_bf16 v[88:91], v[140:143], v[198:201], 0
	v_mfma_f32_16x16x32_bf16 v[76:79], v[132:135], v[214:217], 0
	v_mfma_f32_16x16x32_bf16 v[80:83], v[140:143], v[214:217], 0
	v_mfma_f32_16x16x32_bf16 v[128:131], v[136:139], v[186:189], v[128:131]
	v_mfma_f32_16x16x32_bf16 v[124:127], v[144:147], v[186:189], v[124:127]
	v_mfma_f32_16x16x32_bf16 v[108:111], v[136:139], v[194:197], v[108:111]
	v_mfma_f32_16x16x32_bf16 v[116:119], v[144:147], v[194:197], v[116:119]
	v_mfma_f32_16x16x32_bf16 v[92:95], v[136:139], v[202:205], v[92:95]
	v_mfma_f32_16x16x32_bf16 v[88:91], v[144:147], v[202:205], v[88:91]
	v_mfma_f32_16x16x32_bf16 v[76:79], v[136:139], v[218:221], v[76:79]
	v_mfma_f32_16x16x32_bf16 v[80:83], v[144:147], v[218:221], v[80:83]
	s_setprio 0
	s_setprio 1
	v_mfma_f32_16x16x32_bf16 v[120:123], v[148:151], v[170:173], 0
	v_mfma_f32_16x16x32_bf16 v[104:107], v[156:159], v[170:173], 0
	v_mfma_f32_16x16x32_bf16 v[100:103], v[148:151], v[190:193], 0
	v_mfma_f32_16x16x32_bf16 v[96:99], v[156:159], v[190:193], 0
	v_mfma_f32_16x16x32_bf16 v[84:87], v[148:151], v[198:201], 0
	v_mfma_f32_16x16x32_bf16 v[72:75], v[156:159], v[198:201], 0
	v_mfma_f32_16x16x32_bf16 v[68:71], v[148:151], v[214:217], 0
	v_mfma_f32_16x16x32_bf16 v[64:67], v[156:159], v[214:217], 0
	v_mfma_f32_16x16x32_bf16 v[120:123], v[152:155], v[186:189], v[120:123]
	v_mfma_f32_16x16x32_bf16 v[104:107], v[160:163], v[186:189], v[104:107]
	v_mfma_f32_16x16x32_bf16 v[100:103], v[152:155], v[194:197], v[100:103]
	v_mfma_f32_16x16x32_bf16 v[96:99], v[160:163], v[194:197], v[96:99]
	v_mfma_f32_16x16x32_bf16 v[84:87], v[152:155], v[202:205], v[84:87]
	v_mfma_f32_16x16x32_bf16 v[72:75], v[160:163], v[202:205], v[72:75]
	v_mfma_f32_16x16x32_bf16 v[68:71], v[152:155], v[218:221], v[68:71]
	v_mfma_f32_16x16x32_bf16 v[64:67], v[160:163], v[218:221], v[64:67]
	s_setprio 0
	s_barrier
	s_add_i32 s25, s25, s64
	v_lshl_add_u64 v[206:207], s[20:21], 0, v[2:3]
	s_mov_b32 m0, s25
	ds_read_b128 v[170:173], v182 offset:16384
	ds_read_b128 v[186:189], v182 offset:17408
	ds_read_b128 v[190:193], v182 offset:18432
	ds_read_b128 v[194:197], v182 offset:19456
	ds_read_b128 v[198:201], v182 offset:20480
	ds_read_b128 v[202:205], v182 offset:21504
	ds_read_b128 v[214:217], v182 offset:22528
	ds_read_b128 v[218:221], v182 offset:23552
	global_load_lds_dwordx4 v[206:207], off
	s_add_i32 m0, s25, 0x2000
	s_add_u32 s26, s20, 0x4000
	v_lshl_add_u64 v[206:207], s[20:21], 0, v[164:165]
	s_addc_u32 s27, s21, 0
	s_add_i32 s25, s50, s64
	global_load_lds_dwordx4 v[206:207], off
	v_lshl_add_u64 v[206:207], s[26:27], 0, v[2:3]
	s_mov_b32 m0, s25
	s_nop 0
	global_load_lds_dwordx4 v[206:207], off
	v_lshl_add_u64 v[206:207], s[26:27], 0, v[164:165]
	s_add_i32 m0, s25, 0x2000
	s_nop 0
	global_load_lds_dwordx4 v[206:207], off
	v_lshl_add_u64 v[206:207], s[22:23], 0, v[2:3]
	s_mov_b32 m0, s65
	s_nop 0
	global_load_lds_dwordx4 v[206:207], off
	v_lshl_add_u64 v[206:207], s[22:23], 0, v[164:165]
	s_mov_b32 m0, s34
	s_nop 0
	global_load_lds_dwordx4 v[206:207], off
	s_waitcnt vmcnt(8)
	s_waitcnt lgkmcnt(0)
	s_barrier
	s_setprio 1
	s_waitcnt lgkmcnt(0)
	v_mfma_f32_16x16x32_bf16 v[60:63], v[132:135], v[170:173], 0
	v_mfma_f32_16x16x32_bf16 v[56:59], v[140:143], v[170:173], 0
	v_mfma_f32_16x16x32_bf16 v[44:47], v[132:135], v[190:193], 0
	v_mfma_f32_16x16x32_bf16 v[48:51], v[140:143], v[190:193], 0
	v_mfma_f32_16x16x32_bf16 v[28:31], v[132:135], v[198:201], 0
	v_mfma_f32_16x16x32_bf16 v[24:27], v[140:143], v[198:201], 0
	v_mfma_f32_16x16x32_bf16 v[112:115], v[132:135], v[214:217], 0
	v_mfma_f32_16x16x32_bf16 v[16:19], v[140:143], v[214:217], 0
	v_mfma_f32_16x16x32_bf16 v[60:63], v[136:139], v[186:189], v[60:63]
	v_mfma_f32_16x16x32_bf16 v[56:59], v[144:147], v[186:189], v[56:59]
	v_mfma_f32_16x16x32_bf16 v[44:47], v[136:139], v[194:197], v[44:47]
	v_mfma_f32_16x16x32_bf16 v[48:51], v[144:147], v[194:197], v[48:51]
	v_mfma_f32_16x16x32_bf16 v[28:31], v[136:139], v[202:205], v[28:31]
	v_mfma_f32_16x16x32_bf16 v[24:27], v[144:147], v[202:205], v[24:27]
	v_mfma_f32_16x16x32_bf16 v[112:115], v[136:139], v[218:221], v[112:115]
	v_mfma_f32_16x16x32_bf16 v[16:19], v[144:147], v[218:221], v[16:19]
	s_setprio 0
	s_setprio 1
	v_mfma_f32_16x16x32_bf16 v[52:55], v[148:151], v[170:173], 0
	v_mfma_f32_16x16x32_bf16 v[40:43], v[156:159], v[170:173], 0
	v_mfma_f32_16x16x32_bf16 v[36:39], v[148:151], v[190:193], 0
	v_mfma_f32_16x16x32_bf16 v[32:35], v[156:159], v[190:193], 0
	v_mfma_f32_16x16x32_bf16 v[20:23], v[148:151], v[198:201], 0
	v_mfma_f32_16x16x32_bf16 v[12:15], v[156:159], v[198:201], 0
	v_mfma_f32_16x16x32_bf16 v[4:7], v[148:151], v[214:217], 0
	v_mfma_f32_16x16x32_bf16 v[8:11], v[156:159], v[214:217], 0
	v_mfma_f32_16x16x32_bf16 v[52:55], v[152:155], v[186:189], v[52:55]
	v_mfma_f32_16x16x32_bf16 v[40:43], v[160:163], v[186:189], v[40:43]
	v_mfma_f32_16x16x32_bf16 v[36:39], v[152:155], v[194:197], v[36:39]
	v_mfma_f32_16x16x32_bf16 v[32:35], v[160:163], v[194:197], v[32:35]
	v_mfma_f32_16x16x32_bf16 v[20:23], v[152:155], v[202:205], v[20:23]
	v_mfma_f32_16x16x32_bf16 v[12:15], v[160:163], v[202:205], v[12:15]
	v_mfma_f32_16x16x32_bf16 v[4:7], v[152:155], v[218:221], v[4:7]
	v_mfma_f32_16x16x32_bf16 v[8:11], v[160:163], v[218:221], v[8:11]
	s_setprio 0
	s_barrier
	s_add_i32 s25, 0, 0x18000
	s_add_i32 s26, 0, 0x1c000
	v_add_u32_e32 v144, s25, v174
	v_add_u32_e32 v160, s26, v174
	ds_read_b128 v[132:135], v144
	ds_read_b128 v[136:139], v144 offset:1024
	ds_read_b128 v[140:143], v144 offset:2048
	ds_read_b128 v[144:147], v144 offset:3072
	ds_read_b128 v[148:151], v160
	ds_read_b128 v[152:155], v160 offset:1024
	ds_read_b128 v[156:159], v160 offset:2048
	ds_read_b128 v[160:163], v160 offset:3072
	s_add_u32 s22, s22, 0x4000
	s_addc_u32 s23, s23, 0
	s_mov_b32 m0, s35
	v_lshl_add_u64 v[206:207], s[22:23], 0, v[2:3]
	ds_read_b128 v[170:173], v182 offset:32768
	ds_read_b128 v[186:189], v182 offset:33792
	ds_read_b128 v[190:193], v182 offset:34816
	ds_read_b128 v[194:197], v182 offset:35840
	ds_read_b128 v[198:201], v182 offset:36864
	ds_read_b128 v[202:205], v182 offset:37888
	ds_read_b128 v[214:217], v182 offset:38912
	ds_read_b128 v[218:221], v182 offset:39936
	global_load_lds_dwordx4 v[206:207], off
	v_lshl_add_u64 v[206:207], s[22:23], 0, v[164:165]
	s_mov_b32 m0, s40
	s_nop 0
	global_load_lds_dwordx4 v[206:207], off
	s_waitcnt vmcnt(8)
	s_waitcnt lgkmcnt(0)
	s_barrier
	s_setprio 1
	s_waitcnt lgkmcnt(0)
	v_mfma_f32_16x16x32_bf16 v[128:131], v[132:135], v[170:173], v[128:131]
	v_mfma_f32_16x16x32_bf16 v[124:127], v[140:143], v[170:173], v[124:127]
	v_mfma_f32_16x16x32_bf16 v[108:111], v[132:135], v[190:193], v[108:111]
	v_mfma_f32_16x16x32_bf16 v[116:119], v[140:143], v[190:193], v[116:119]
	v_mfma_f32_16x16x32_bf16 v[92:95], v[132:135], v[198:201], v[92:95]
	v_mfma_f32_16x16x32_bf16 v[88:91], v[140:143], v[198:201], v[88:91]
	v_mfma_f32_16x16x32_bf16 v[76:79], v[132:135], v[214:217], v[76:79]
	v_mfma_f32_16x16x32_bf16 v[80:83], v[140:143], v[214:217], v[80:83]
	v_mfma_f32_16x16x32_bf16 v[128:131], v[136:139], v[186:189], v[128:131]
	v_mfma_f32_16x16x32_bf16 v[124:127], v[144:147], v[186:189], v[124:127]
	v_mfma_f32_16x16x32_bf16 v[108:111], v[136:139], v[194:197], v[108:111]
	v_mfma_f32_16x16x32_bf16 v[116:119], v[144:147], v[194:197], v[116:119]
	v_mfma_f32_16x16x32_bf16 v[92:95], v[136:139], v[202:205], v[92:95]
	v_mfma_f32_16x16x32_bf16 v[88:91], v[144:147], v[202:205], v[88:91]
	v_mfma_f32_16x16x32_bf16 v[76:79], v[136:139], v[218:221], v[76:79]
	v_mfma_f32_16x16x32_bf16 v[80:83], v[144:147], v[218:221], v[80:83]
	s_setprio 0
	s_setprio 1
	v_mfma_f32_16x16x32_bf16 v[120:123], v[148:151], v[170:173], v[120:123]
	v_mfma_f32_16x16x32_bf16 v[104:107], v[156:159], v[170:173], v[104:107]
	v_mfma_f32_16x16x32_bf16 v[100:103], v[148:151], v[190:193], v[100:103]
	v_mfma_f32_16x16x32_bf16 v[96:99], v[156:159], v[190:193], v[96:99]
	v_mfma_f32_16x16x32_bf16 v[84:87], v[148:151], v[198:201], v[84:87]
	v_mfma_f32_16x16x32_bf16 v[72:75], v[156:159], v[198:201], v[72:75]
	v_mfma_f32_16x16x32_bf16 v[68:71], v[148:151], v[214:217], v[68:71]
	v_mfma_f32_16x16x32_bf16 v[64:67], v[156:159], v[214:217], v[64:67]
	v_mfma_f32_16x16x32_bf16 v[120:123], v[152:155], v[186:189], v[120:123]
	v_mfma_f32_16x16x32_bf16 v[104:107], v[160:163], v[186:189], v[104:107]
	v_mfma_f32_16x16x32_bf16 v[100:103], v[152:155], v[194:197], v[100:103]
	v_mfma_f32_16x16x32_bf16 v[96:99], v[160:163], v[194:197], v[96:99]
	v_mfma_f32_16x16x32_bf16 v[84:87], v[152:155], v[202:205], v[84:87]
	v_mfma_f32_16x16x32_bf16 v[72:75], v[160:163], v[202:205], v[72:75]
	v_mfma_f32_16x16x32_bf16 v[68:71], v[152:155], v[218:221], v[68:71]
	v_mfma_f32_16x16x32_bf16 v[64:67], v[160:163], v[218:221], v[64:67]
	s_setprio 0
	s_barrier
	s_add_u32 s22, s20, 0x8000
	s_addc_u32 s23, s21, 0
	s_add_i32 s25, s25, s64
	v_lshl_add_u64 v[206:207], s[22:23], 0, v[2:3]
	s_mov_b32 m0, s25
	ds_read_b128 v[170:173], v182 offset:49152
	ds_read_b128 v[186:189], v182 offset:50176
	ds_read_b128 v[190:193], v182 offset:51200
	ds_read_b128 v[194:197], v182 offset:52224
	ds_read_b128 v[198:201], v182 offset:53248
	ds_read_b128 v[202:205], v182 offset:54272
	ds_read_b128 v[214:217], v182 offset:55296
	ds_read_b128 v[218:221], v182 offset:56320
	global_load_lds_dwordx4 v[206:207], off
	s_add_i32 m0, s25, 0x2000
	s_add_u32 s20, s20, 0xc000
	v_lshl_add_u64 v[206:207], s[22:23], 0, v[164:165]
	s_addc_u32 s21, s21, 0
	s_add_i32 s22, s26, s64
	global_load_lds_dwordx4 v[206:207], off
	v_lshl_add_u64 v[206:207], s[20:21], 0, v[2:3]
	s_mov_b32 m0, s22
	s_nop 0
	global_load_lds_dwordx4 v[206:207], off
	v_lshl_add_u64 v[206:207], s[20:21], 0, v[164:165]
	s_add_i32 m0, s22, 0x2000
	s_nop 0
	global_load_lds_dwordx4 v[206:207], off
	v_lshl_add_u64 v[206:207], s[14:15], 0, v[2:3]
	s_mov_b32 m0, s41
	s_nop 0
	global_load_lds_dwordx4 v[206:207], off
	v_lshl_add_u64 v[206:207], s[14:15], 0, v[164:165]
	s_mov_b32 m0, s46
	s_nop 0
	global_load_lds_dwordx4 v[206:207], off
	s_waitcnt vmcnt(8)
	s_waitcnt lgkmcnt(0)
	s_barrier
	s_setprio 1
	s_waitcnt lgkmcnt(0)
	v_mfma_f32_16x16x32_bf16 v[60:63], v[132:135], v[170:173], v[60:63]
	v_mfma_f32_16x16x32_bf16 v[56:59], v[140:143], v[170:173], v[56:59]
	v_mfma_f32_16x16x32_bf16 v[44:47], v[132:135], v[190:193], v[44:47]
	v_mfma_f32_16x16x32_bf16 v[48:51], v[140:143], v[190:193], v[48:51]
	v_mfma_f32_16x16x32_bf16 v[28:31], v[132:135], v[198:201], v[28:31]
	v_mfma_f32_16x16x32_bf16 v[24:27], v[140:143], v[198:201], v[24:27]
	v_mfma_f32_16x16x32_bf16 v[112:115], v[132:135], v[214:217], v[112:115]
	v_mfma_f32_16x16x32_bf16 v[16:19], v[140:143], v[214:217], v[16:19]
	v_mfma_f32_16x16x32_bf16 v[60:63], v[136:139], v[186:189], v[60:63]
	v_mfma_f32_16x16x32_bf16 v[56:59], v[144:147], v[186:189], v[56:59]
	v_mfma_f32_16x16x32_bf16 v[44:47], v[136:139], v[194:197], v[44:47]
	v_mfma_f32_16x16x32_bf16 v[48:51], v[144:147], v[194:197], v[48:51]
	v_mfma_f32_16x16x32_bf16 v[28:31], v[136:139], v[202:205], v[28:31]
	v_mfma_f32_16x16x32_bf16 v[24:27], v[144:147], v[202:205], v[24:27]
	v_mfma_f32_16x16x32_bf16 v[112:115], v[136:139], v[218:221], v[112:115]
	v_mfma_f32_16x16x32_bf16 v[16:19], v[144:147], v[218:221], v[16:19]
	s_setprio 0
	s_setprio 1
	v_mfma_f32_16x16x32_bf16 v[52:55], v[148:151], v[170:173], v[52:55]
	v_mfma_f32_16x16x32_bf16 v[40:43], v[156:159], v[170:173], v[40:43]
	v_mfma_f32_16x16x32_bf16 v[36:39], v[148:151], v[190:193], v[36:39]
	v_mfma_f32_16x16x32_bf16 v[32:35], v[156:159], v[190:193], v[32:35]
	v_mfma_f32_16x16x32_bf16 v[20:23], v[148:151], v[198:201], v[20:23]
	v_mfma_f32_16x16x32_bf16 v[12:15], v[156:159], v[198:201], v[12:15]
	v_mfma_f32_16x16x32_bf16 v[4:7], v[148:151], v[214:217], v[4:7]
	v_mfma_f32_16x16x32_bf16 v[8:11], v[156:159], v[214:217], v[8:11]
	v_mfma_f32_16x16x32_bf16 v[52:55], v[152:155], v[186:189], v[52:55]
	v_mfma_f32_16x16x32_bf16 v[40:43], v[160:163], v[186:189], v[40:43]
	v_mfma_f32_16x16x32_bf16 v[36:39], v[152:155], v[194:197], v[36:39]
	v_mfma_f32_16x16x32_bf16 v[32:35], v[160:163], v[194:197], v[32:35]
	v_mfma_f32_16x16x32_bf16 v[20:23], v[152:155], v[202:205], v[20:23]
	v_mfma_f32_16x16x32_bf16 v[12:15], v[160:163], v[202:205], v[12:15]
	v_mfma_f32_16x16x32_bf16 v[4:7], v[152:155], v[218:221], v[4:7]
	v_mfma_f32_16x16x32_bf16 v[8:11], v[160:163], v[218:221], v[8:11]
	s_setprio 0
	s_barrier
	s_add_i32 s24, s24, 2
	s_add_u32 s18, s18, 0x10000
	s_addc_u32 s19, s19, 0
	s_add_u32 s2, s2, 0x10000
	s_addc_u32 s3, s3, 0
	s_cmpk_gt_u32 s24, 0x55

.LBB0_337:
	s_ashr_i32 s5, s4, 31
	s_lshl_b64 s[16:17], s[4:5], 20
	s_add_u32 s16, s31, s16
	s_addc_u32 s17, s34, s17
	s_and_b64 s[20:21], s[10:11], exec
	s_cselect_b32 s5, s17, s23
	s_cselect_b32 s15, s16, s22
	s_ashr_i32 s7, s6, 31
	s_lshl_b64 s[20:21], s[6:7], 20
	s_add_u32 s20, s35, s20
	s_addc_u32 s21, s36, s21
	s_and_b64 s[24:25], s[10:11], exec
	s_cselect_b32 s7, s21, s13
	s_cselect_b32 s26, s20, s12
	s_add_u32 s27, s12, 0x10000
	s_addc_u32 s50, s13, 0
	s_add_u32 s12, s22, 0x80080
	s_addc_u32 s13, s23, 0
	s_mov_b32 s51, -2
	s_add_u32 s22, s12, 0xfff80080
	s_addc_u32 s23, s13, -1
	s_add_i32 s52, 0, 0x10000
	s_cmp_eq_u32 s51, 28
	s_cselect_b32 s25, s5, s23
	s_cselect_b32 s24, s15, s22
	v_add_u32_e32 v2, s52, v205
	s_cselect_b32 s23, s7, s50
	s_cselect_b32 s22, s26, s27
	s_add_i32 s54, 0, 0x14000
	ds_read_b128 v[92:95], v2
	ds_read_b128 v[96:99], v2 offset:1024
	ds_read_b128 v[120:123], v2 offset:2048
	ds_read_b128 v[132:135], v2 offset:3072
	v_add_u32_e32 v2, s54, v205
	ds_read_b128 v[140:143], v2
	ds_read_b128 v[152:155], v2 offset:1024
	ds_read_b128 v[156:159], v2 offset:2048
	ds_read_b128 v[160:163], v2 offset:3072
	v_lshl_add_u64 v[206:207], s[12:13], 0, v[220:221]
	s_add_i32 m0, s19, 0xc000
	ds_read_b128 v[164:167], v215
	ds_read_b128 v[168:171], v215 offset:1024
	ds_read_b128 v[172:175], v215 offset:2048
	ds_read_b128 v[176:179], v215 offset:3072
	ds_read_b128 v[180:183], v215 offset:4096
	ds_read_b128 v[184:187], v215 offset:5120
	ds_read_b128 v[188:191], v215 offset:6144
	ds_read_b128 v[192:195], v215 offset:7168
	global_load_lds_dwordx4 v[206:207], off
	v_lshl_add_u64 v[206:207], s[12:13], 0, v[222:223]
	s_add_i32 m0, s19, 0xe000
	s_nop 0
	global_load_lds_dwordx4 v[206:207], off
	s_waitcnt vmcnt(8)
	s_waitcnt lgkmcnt(0)
	s_barrier
	s_setprio 1
	s_waitcnt lgkmcnt(0)
	v_mfma_f32_16x16x32_bf16 v[148:151], v[92:95], v[164:167], 0
	v_mfma_f32_16x16x32_bf16 v[144:147], v[120:123], v[164:167], 0
	v_mfma_f32_16x16x32_bf16 v[124:127], v[92:95], v[172:175], 0
	v_mfma_f32_16x16x32_bf16 v[116:119], v[120:123], v[172:175], 0
	v_mfma_f32_16x16x32_bf16 v[104:107], v[92:95], v[180:183], 0
	v_mfma_f32_16x16x32_bf16 v[100:103], v[120:123], v[180:183], 0
	v_mfma_f32_16x16x32_bf16 v[80:83], v[92:95], v[188:191], 0
	v_mfma_f32_16x16x32_bf16 v[76:79], v[120:123], v[188:191], 0
	v_mfma_f32_16x16x32_bf16 v[148:151], v[96:99], v[168:171], v[148:151]
	v_mfma_f32_16x16x32_bf16 v[144:147], v[132:135], v[168:171], v[144:147]
	v_mfma_f32_16x16x32_bf16 v[124:127], v[96:99], v[176:179], v[124:127]
	v_mfma_f32_16x16x32_bf16 v[116:119], v[132:135], v[176:179], v[116:119]
	v_mfma_f32_16x16x32_bf16 v[104:107], v[96:99], v[184:187], v[104:107]
	v_mfma_f32_16x16x32_bf16 v[100:103], v[132:135], v[184:187], v[100:103]
	v_mfma_f32_16x16x32_bf16 v[80:83], v[96:99], v[192:195], v[80:83]
	v_mfma_f32_16x16x32_bf16 v[76:79], v[132:135], v[192:195], v[76:79]
	s_setprio 0
	s_setprio 1
	v_mfma_f32_16x16x32_bf16 v[136:139], v[140:143], v[164:167], 0
	v_mfma_f32_16x16x32_bf16 v[128:131], v[156:159], v[164:167], 0
	v_mfma_f32_16x16x32_bf16 v[112:115], v[140:143], v[172:175], 0
	v_mfma_f32_16x16x32_bf16 v[108:111], v[156:159], v[172:175], 0
	v_mfma_f32_16x16x32_bf16 v[88:91], v[140:143], v[180:183], 0
	v_mfma_f32_16x16x32_bf16 v[84:87], v[156:159], v[180:183], 0
	v_mfma_f32_16x16x32_bf16 v[72:75], v[140:143], v[188:191], 0
	v_mfma_f32_16x16x32_bf16 v[68:71], v[156:159], v[188:191], 0
	v_mfma_f32_16x16x32_bf16 v[136:139], v[152:155], v[168:171], v[136:139]
	v_mfma_f32_16x16x32_bf16 v[128:131], v[160:163], v[168:171], v[128:131]
	v_mfma_f32_16x16x32_bf16 v[112:115], v[152:155], v[176:179], v[112:115]
	v_mfma_f32_16x16x32_bf16 v[108:111], v[160:163], v[176:179], v[108:111]
	v_mfma_f32_16x16x32_bf16 v[88:91], v[152:155], v[184:187], v[88:91]
	v_mfma_f32_16x16x32_bf16 v[84:87], v[160:163], v[184:187], v[84:87]
	v_mfma_f32_16x16x32_bf16 v[72:75], v[152:155], v[192:195], v[72:75]
	v_mfma_f32_16x16x32_bf16 v[68:71], v[160:163], v[192:195], v[68:71]
	s_setprio 0
	s_barrier
	s_add_i32 s52, s52, s37
	v_lshl_add_u64 v[206:207], s[22:23], 0, v[198:199]
	s_mov_b32 m0, s52
	ds_read_b128 v[164:167], v215 offset:16384
	ds_read_b128 v[168:171], v215 offset:17408
	ds_read_b128 v[172:175], v215 offset:18432
	ds_read_b128 v[176:179], v215 offset:19456
	ds_read_b128 v[180:183], v215 offset:20480
	ds_read_b128 v[184:187], v215 offset:21504
	ds_read_b128 v[188:191], v215 offset:22528
	ds_read_b128 v[192:195], v215 offset:23552
	global_load_lds_dwordx4 v[206:207], off
	s_add_i32 m0, s52, 0x2000
	s_add_u32 s52, s22, 0x4000
	v_lshl_add_u64 v[206:207], s[22:23], 0, v[202:203]
	s_addc_u32 s53, s23, 0
	s_add_i32 s54, s54, s37
	global_load_lds_dwordx4 v[206:207], off
	v_lshl_add_u64 v[206:207], s[52:53], 0, v[198:199]
	s_mov_b32 m0, s54
	v_lshl_add_u64 v[208:209], s[24:25], 0, v[200:201]
	global_load_lds_dwordx4 v[206:207], off
	v_lshl_add_u64 v[206:207], s[52:53], 0, v[202:203]
	s_add_i32 m0, s54, 0x2000
	s_nop 0
	global_load_lds_dwordx4 v[206:207], off
	v_lshl_add_u64 v[206:207], s[24:25], 0, v[196:197]
	s_mov_b32 m0, s19
	s_nop 0
	global_load_lds_dwordx4 v[206:207], off
	s_mov_b32 m0, s38
	s_nop 0
	global_load_lds_dwordx4 v[208:209], off
	s_waitcnt vmcnt(8)
	s_waitcnt lgkmcnt(0)
	s_barrier
	s_setprio 1
	s_waitcnt lgkmcnt(0)
	v_mfma_f32_16x16x32_bf16 v[64:67], v[92:95], v[164:167], 0
	v_mfma_f32_16x16x32_bf16 v[60:63], v[120:123], v[164:167], 0
	v_mfma_f32_16x16x32_bf16 v[48:51], v[92:95], v[172:175], 0
	v_mfma_f32_16x16x32_bf16 v[44:47], v[120:123], v[172:175], 0
	v_mfma_f32_16x16x32_bf16 v[32:35], v[92:95], v[180:183], 0
	v_mfma_f32_16x16x32_bf16 v[28:31], v[120:123], v[180:183], 0
	v_mfma_f32_16x16x32_bf16 v[16:19], v[92:95], v[188:191], 0
	v_mfma_f32_16x16x32_bf16 v[12:15], v[120:123], v[188:191], 0
	v_mfma_f32_16x16x32_bf16 v[64:67], v[96:99], v[168:171], v[64:67]
	v_mfma_f32_16x16x32_bf16 v[60:63], v[132:135], v[168:171], v[60:63]
	v_mfma_f32_16x16x32_bf16 v[48:51], v[96:99], v[176:179], v[48:51]
	v_mfma_f32_16x16x32_bf16 v[44:47], v[132:135], v[176:179], v[44:47]
	v_mfma_f32_16x16x32_bf16 v[32:35], v[96:99], v[184:187], v[32:35]
	v_mfma_f32_16x16x32_bf16 v[28:31], v[132:135], v[184:187], v[28:31]
	v_mfma_f32_16x16x32_bf16 v[16:19], v[96:99], v[192:195], v[16:19]
	v_mfma_f32_16x16x32_bf16 v[12:15], v[132:135], v[192:195], v[12:15]
	s_setprio 0
	s_setprio 1
	v_mfma_f32_16x16x32_bf16 v[56:59], v[140:143], v[164:167], 0
	v_mfma_f32_16x16x32_bf16 v[52:55], v[156:159], v[164:167], 0
	v_mfma_f32_16x16x32_bf16 v[40:43], v[140:143], v[172:175], 0
	v_mfma_f32_16x16x32_bf16 v[36:39], v[156:159], v[172:175], 0
	v_mfma_f32_16x16x32_bf16 v[24:27], v[140:143], v[180:183], 0
	v_mfma_f32_16x16x32_bf16 v[20:23], v[156:159], v[180:183], 0
	v_mfma_f32_16x16x32_bf16 v[8:11], v[140:143], v[188:191], 0
	v_mfma_f32_16x16x32_bf16 v[4:7], v[156:159], v[188:191], 0
	v_mfma_f32_16x16x32_bf16 v[56:59], v[152:155], v[168:171], v[56:59]
	v_mfma_f32_16x16x32_bf16 v[52:55], v[160:163], v[168:171], v[52:55]
	v_mfma_f32_16x16x32_bf16 v[40:43], v[152:155], v[176:179], v[40:43]
	v_mfma_f32_16x16x32_bf16 v[36:39], v[160:163], v[176:179], v[36:39]
	v_mfma_f32_16x16x32_bf16 v[24:27], v[152:155], v[184:187], v[24:27]
	v_mfma_f32_16x16x32_bf16 v[20:23], v[160:163], v[184:187], v[20:23]
	v_mfma_f32_16x16x32_bf16 v[8:11], v[152:155], v[192:195], v[8:11]
	v_mfma_f32_16x16x32_bf16 v[4:7], v[160:163], v[192:195], v[4:7]
	s_setprio 0
	s_barrier
	s_add_i32 s52, 0, 0x18000
	v_add_u32_e32 v2, s52, v205
	s_add_i32 s53, 0, 0x1c000
	ds_read_b128 v[92:95], v2
	ds_read_b128 v[96:99], v2 offset:1024
	ds_read_b128 v[120:123], v2 offset:2048
	ds_read_b128 v[132:135], v2 offset:3072
	v_add_u32_e32 v2, s53, v205
	ds_read_b128 v[140:143], v2
	ds_read_b128 v[152:155], v2 offset:1024
	ds_read_b128 v[156:159], v2 offset:2048
	ds_read_b128 v[160:163], v2 offset:3072
	s_add_u32 s24, s24, 0x80000
	s_addc_u32 s25, s25, 0
	s_mov_b32 m0, s39
	v_lshl_add_u64 v[210:211], s[24:25], 0, v[196:197]
	ds_read_b128 v[164:167], v215 offset:32768
	ds_read_b128 v[168:171], v215 offset:33792
	ds_read_b128 v[172:175], v215 offset:34816
	ds_read_b128 v[176:179], v215 offset:35840
	ds_read_b128 v[180:183], v215 offset:36864
	ds_read_b128 v[184:187], v215 offset:37888
	ds_read_b128 v[188:191], v215 offset:38912
	ds_read_b128 v[192:195], v215 offset:39936
	global_load_lds_dwordx4 v[210:211], off
	v_lshl_add_u64 v[210:211], s[24:25], 0, v[200:201]
	s_mov_b32 m0, s40
	s_nop 0
	global_load_lds_dwordx4 v[210:211], off
	s_waitcnt vmcnt(8)
	s_waitcnt lgkmcnt(0)
	s_barrier
	s_setprio 1
	s_waitcnt lgkmcnt(0)
	v_mfma_f32_16x16x32_bf16 v[148:151], v[92:95], v[164:167], v[148:151]
	v_mfma_f32_16x16x32_bf16 v[144:147], v[120:123], v[164:167], v[144:147]
	v_mfma_f32_16x16x32_bf16 v[124:127], v[92:95], v[172:175], v[124:127]
	v_mfma_f32_16x16x32_bf16 v[116:119], v[120:123], v[172:175], v[116:119]
	v_mfma_f32_16x16x32_bf16 v[104:107], v[92:95], v[180:183], v[104:107]
	v_mfma_f32_16x16x32_bf16 v[100:103], v[120:123], v[180:183], v[100:103]
	v_mfma_f32_16x16x32_bf16 v[80:83], v[92:95], v[188:191], v[80:83]
	v_mfma_f32_16x16x32_bf16 v[76:79], v[120:123], v[188:191], v[76:79]
	v_mfma_f32_16x16x32_bf16 v[148:151], v[96:99], v[168:171], v[148:151]
	v_mfma_f32_16x16x32_bf16 v[144:147], v[132:135], v[168:171], v[144:147]
	v_mfma_f32_16x16x32_bf16 v[124:127], v[96:99], v[176:179], v[124:127]
	v_mfma_f32_16x16x32_bf16 v[116:119], v[132:135], v[176:179], v[116:119]
	v_mfma_f32_16x16x32_bf16 v[104:107], v[96:99], v[184:187], v[104:107]
	v_mfma_f32_16x16x32_bf16 v[100:103], v[132:135], v[184:187], v[100:103]
	v_mfma_f32_16x16x32_bf16 v[80:83], v[96:99], v[192:195], v[80:83]
	v_mfma_f32_16x16x32_bf16 v[76:79], v[132:135], v[192:195], v[76:79]
	s_setprio 0
	s_setprio 1
	v_mfma_f32_16x16x32_bf16 v[136:139], v[140:143], v[164:167], v[136:139]
	v_mfma_f32_16x16x32_bf16 v[128:131], v[156:159], v[164:167], v[128:131]
	v_mfma_f32_16x16x32_bf16 v[112:115], v[140:143], v[172:175], v[112:115]
	v_mfma_f32_16x16x32_bf16 v[108:111], v[156:159], v[172:175], v[108:111]
	v_mfma_f32_16x16x32_bf16 v[88:91], v[140:143], v[180:183], v[88:91]
	v_mfma_f32_16x16x32_bf16 v[84:87], v[156:159], v[180:183], v[84:87]
	v_mfma_f32_16x16x32_bf16 v[72:75], v[140:143], v[188:191], v[72:75]
	v_mfma_f32_16x16x32_bf16 v[68:71], v[156:159], v[188:191], v[68:71]
	v_mfma_f32_16x16x32_bf16 v[136:139], v[152:155], v[168:171], v[136:139]
	v_mfma_f32_16x16x32_bf16 v[128:131], v[160:163], v[168:171], v[128:131]
	v_mfma_f32_16x16x32_bf16 v[112:115], v[152:155], v[176:179], v[112:115]
	v_mfma_f32_16x16x32_bf16 v[108:111], v[160:163], v[176:179], v[108:111]
	v_mfma_f32_16x16x32_bf16 v[88:91], v[152:155], v[184:187], v[88:91]
	v_mfma_f32_16x16x32_bf16 v[84:87], v[160:163], v[184:187], v[84:87]
	v_mfma_f32_16x16x32_bf16 v[72:75], v[152:155], v[192:195], v[72:75]
	v_mfma_f32_16x16x32_bf16 v[68:71], v[160:163], v[192:195], v[68:71]
	s_setprio 0
	s_barrier
	s_add_u32 s24, s22, 0x8000
	s_addc_u32 s25, s23, 0
	s_add_i32 s52, s52, s37
	v_lshl_add_u64 v[210:211], s[24:25], 0, v[198:199]
	s_mov_b32 m0, s52
	ds_read_b128 v[164:167], v215 offset:49152
	ds_read_b128 v[168:171], v215 offset:50176
	ds_read_b128 v[172:175], v215 offset:51200
	ds_read_b128 v[176:179], v215 offset:52224
	ds_read_b128 v[180:183], v215 offset:53248
	ds_read_b128 v[184:187], v215 offset:54272
	ds_read_b128 v[188:191], v215 offset:55296
	ds_read_b128 v[192:195], v215 offset:56320
	global_load_lds_dwordx4 v[210:211], off
	s_add_i32 m0, s52, 0x2000
	s_add_u32 s22, s22, 0xc000
	v_lshl_add_u64 v[210:211], s[24:25], 0, v[202:203]
	s_addc_u32 s23, s23, 0
	s_add_i32 s24, s53, s37
	global_load_lds_dwordx4 v[210:211], off
	v_lshl_add_u64 v[210:211], s[22:23], 0, v[198:199]
	s_mov_b32 m0, s24
	v_lshl_add_u64 v[206:207], v[206:207], 0, s[74:75]
	global_load_lds_dwordx4 v[210:211], off
	v_lshl_add_u64 v[210:211], s[22:23], 0, v[202:203]
	s_add_i32 m0, s24, 0x2000
	s_nop 0
	global_load_lds_dwordx4 v[210:211], off
	s_mov_b32 m0, s47
	s_nop 0
	global_load_lds_dwordx4 v[206:207], off
	v_lshl_add_u64 v[206:207], v[208:209], 0, s[74:75]
	s_mov_b32 m0, s48
	s_nop 0
	global_load_lds_dwordx4 v[206:207], off
	s_waitcnt vmcnt(8)
	s_waitcnt lgkmcnt(0)
	s_barrier
	s_setprio 1
	s_waitcnt lgkmcnt(0)
	v_mfma_f32_16x16x32_bf16 v[64:67], v[92:95], v[164:167], v[64:67]
	v_mfma_f32_16x16x32_bf16 v[60:63], v[120:123], v[164:167], v[60:63]
	v_mfma_f32_16x16x32_bf16 v[48:51], v[92:95], v[172:175], v[48:51]
	v_mfma_f32_16x16x32_bf16 v[44:47], v[120:123], v[172:175], v[44:47]
	v_mfma_f32_16x16x32_bf16 v[32:35], v[92:95], v[180:183], v[32:35]
	v_mfma_f32_16x16x32_bf16 v[28:31], v[120:123], v[180:183], v[28:31]
	v_mfma_f32_16x16x32_bf16 v[16:19], v[92:95], v[188:191], v[16:19]
	v_mfma_f32_16x16x32_bf16 v[12:15], v[120:123], v[188:191], v[12:15]
	v_mfma_f32_16x16x32_bf16 v[64:67], v[96:99], v[168:171], v[64:67]
	v_mfma_f32_16x16x32_bf16 v[60:63], v[132:135], v[168:171], v[60:63]
	v_mfma_f32_16x16x32_bf16 v[48:51], v[96:99], v[176:179], v[48:51]
	v_mfma_f32_16x16x32_bf16 v[44:47], v[132:135], v[176:179], v[44:47]
	v_mfma_f32_16x16x32_bf16 v[32:35], v[96:99], v[184:187], v[32:35]
	v_mfma_f32_16x16x32_bf16 v[28:31], v[132:135], v[184:187], v[28:31]
	v_mfma_f32_16x16x32_bf16 v[16:19], v[96:99], v[192:195], v[16:19]
	v_mfma_f32_16x16x32_bf16 v[12:15], v[132:135], v[192:195], v[12:15]
	s_setprio 0
	s_setprio 1
	v_mfma_f32_16x16x32_bf16 v[56:59], v[140:143], v[164:167], v[56:59]
	v_mfma_f32_16x16x32_bf16 v[52:55], v[156:159], v[164:167], v[52:55]
	v_mfma_f32_16x16x32_bf16 v[40:43], v[140:143], v[172:175], v[40:43]
	v_mfma_f32_16x16x32_bf16 v[36:39], v[156:159], v[172:175], v[36:39]
	v_mfma_f32_16x16x32_bf16 v[24:27], v[140:143], v[180:183], v[24:27]
	v_mfma_f32_16x16x32_bf16 v[20:23], v[156:159], v[180:183], v[20:23]
	v_mfma_f32_16x16x32_bf16 v[8:11], v[140:143], v[188:191], v[8:11]
	v_mfma_f32_16x16x32_bf16 v[4:7], v[156:159], v[188:191], v[4:7]
	v_mfma_f32_16x16x32_bf16 v[56:59], v[152:155], v[168:171], v[56:59]
	v_mfma_f32_16x16x32_bf16 v[52:55], v[160:163], v[168:171], v[52:55]
	v_mfma_f32_16x16x32_bf16 v[40:43], v[152:155], v[176:179], v[40:43]
	v_mfma_f32_16x16x32_bf16 v[36:39], v[160:163], v[176:179], v[36:39]
	v_mfma_f32_16x16x32_bf16 v[24:27], v[152:155], v[184:187], v[24:27]
	v_mfma_f32_16x16x32_bf16 v[20:23], v[160:163], v[184:187], v[20:23]
	v_mfma_f32_16x16x32_bf16 v[8:11], v[152:155], v[192:195], v[8:11]
	v_mfma_f32_16x16x32_bf16 v[4:7], v[160:163], v[192:195], v[4:7]
	s_setprio 0
	s_barrier
	s_add_i32 s51, s51, 2
	s_add_u32 s27, s27, 0x10000
	s_addc_u32 s50, s50, 0
	s_add_u32 s12, s12, 0x100
	s_addc_u32 s13, s13, 0
	s_cmp_gt_u32 s51, 29

.LBB0_639:
	s_ashr_i32 s5, s4, 31
	s_lshl_b64 s[24:25], s[4:5], 20
	v_readlane_b32 s5, v254, 27
	s_add_u32 s36, s5, s24
	s_addc_u32 s37, s33, s25
	s_and_b64 s[24:25], s[16:17], exec
	s_cselect_b32 s5, s37, s23
	s_cselect_b32 s19, s36, s22
	s_ashr_i32 s49, s48, 31
	s_lshl_b64 s[24:25], s[48:49], 20
	v_readlane_b32 s26, v254, 46
	s_add_u32 s42, s26, s24
	v_readlane_b32 s24, v254, 48
	s_addc_u32 s43, s24, s25
	s_and_b64 s[24:25], s[16:17], exec
	s_cselect_b32 s26, s43, s21
	s_cselect_b32 s27, s42, s20
	s_add_u32 s29, s20, 0x10000
	s_addc_u32 s49, s21, 0
	s_add_u32 s20, s22, 0x80080
	s_addc_u32 s21, s23, 0
	s_mov_b32 s54, -2
	s_add_u32 s22, s20, 0xfff80080
	s_addc_u32 s23, s21, -1
	s_add_i32 s55, 0, 0x10000
	s_cmp_eq_u32 s54, 28
	s_cselect_b32 s25, s5, s23
	s_cselect_b32 s24, s19, s22
	s_cselect_b32 s23, s26, s49
	s_cselect_b32 s22, s27, s29
	s_add_i32 s63, 0, 0x14000
	v_add_u32_e32 v144, s55, v178
	v_add_u32_e32 v160, s63, v178
	ds_read_b128 v[132:135], v144
	ds_read_b128 v[136:139], v144 offset:1024
	ds_read_b128 v[140:143], v144 offset:2048
	ds_read_b128 v[144:147], v144 offset:3072
	ds_read_b128 v[148:151], v160
	ds_read_b128 v[152:155], v160 offset:1024
	ds_read_b128 v[156:159], v160 offset:2048
	ds_read_b128 v[160:163], v160 offset:3072
	v_lshl_add_u64 v[206:207], s[20:21], 0, v[170:171]
	s_add_i32 m0, s39, 0xc000
	ds_read_b128 v[174:177], v186
	ds_read_b128 v[190:193], v186 offset:1024
	ds_read_b128 v[194:197], v186 offset:2048
	ds_read_b128 v[198:201], v186 offset:3072
	ds_read_b128 v[202:205], v186 offset:4096
	ds_read_b128 v[214:217], v186 offset:5120
	ds_read_b128 v[218:221], v186 offset:6144
	ds_read_b128 v[222:225], v186 offset:7168
	global_load_lds_dwordx4 v[206:207], off
	v_lshl_add_u64 v[206:207], s[20:21], 0, v[172:173]
	s_add_i32 m0, s39, 0xe000
	s_nop 0
	global_load_lds_dwordx4 v[206:207], off
	s_waitcnt vmcnt(8)
	s_waitcnt lgkmcnt(0)
	s_barrier
	s_setprio 1
	s_waitcnt lgkmcnt(0)
	v_mfma_f32_16x16x32_bf16 v[128:131], v[132:135], v[174:177], 0
	v_mfma_f32_16x16x32_bf16 v[124:127], v[140:143], v[174:177], 0
	v_mfma_f32_16x16x32_bf16 v[108:111], v[132:135], v[194:197], 0
	v_mfma_f32_16x16x32_bf16 v[116:119], v[140:143], v[194:197], 0
	v_mfma_f32_16x16x32_bf16 v[92:95], v[132:135], v[202:205], 0
	v_mfma_f32_16x16x32_bf16 v[88:91], v[140:143], v[202:205], 0
	v_mfma_f32_16x16x32_bf16 v[76:79], v[132:135], v[218:221], 0
	v_mfma_f32_16x16x32_bf16 v[80:83], v[140:143], v[218:221], 0
	v_mfma_f32_16x16x32_bf16 v[128:131], v[136:139], v[190:193], v[128:131]
	v_mfma_f32_16x16x32_bf16 v[124:127], v[144:147], v[190:193], v[124:127]
	v_mfma_f32_16x16x32_bf16 v[108:111], v[136:139], v[198:201], v[108:111]
	v_mfma_f32_16x16x32_bf16 v[116:119], v[144:147], v[198:201], v[116:119]
	v_mfma_f32_16x16x32_bf16 v[92:95], v[136:139], v[214:217], v[92:95]
	v_mfma_f32_16x16x32_bf16 v[88:91], v[144:147], v[214:217], v[88:91]
	v_mfma_f32_16x16x32_bf16 v[76:79], v[136:139], v[222:225], v[76:79]
	v_mfma_f32_16x16x32_bf16 v[80:83], v[144:147], v[222:225], v[80:83]
	s_setprio 0
	s_setprio 1
	v_mfma_f32_16x16x32_bf16 v[120:123], v[148:151], v[174:177], 0
	v_mfma_f32_16x16x32_bf16 v[104:107], v[156:159], v[174:177], 0
	v_mfma_f32_16x16x32_bf16 v[100:103], v[148:151], v[194:197], 0
	v_mfma_f32_16x16x32_bf16 v[96:99], v[156:159], v[194:197], 0
	v_mfma_f32_16x16x32_bf16 v[84:87], v[148:151], v[202:205], 0
	v_mfma_f32_16x16x32_bf16 v[72:75], v[156:159], v[202:205], 0
	v_mfma_f32_16x16x32_bf16 v[68:71], v[148:151], v[218:221], 0
	v_mfma_f32_16x16x32_bf16 v[64:67], v[156:159], v[218:221], 0
	v_mfma_f32_16x16x32_bf16 v[120:123], v[152:155], v[190:193], v[120:123]
	v_mfma_f32_16x16x32_bf16 v[104:107], v[160:163], v[190:193], v[104:107]
	v_mfma_f32_16x16x32_bf16 v[100:103], v[152:155], v[198:201], v[100:103]
	v_mfma_f32_16x16x32_bf16 v[96:99], v[160:163], v[198:201], v[96:99]
	v_mfma_f32_16x16x32_bf16 v[84:87], v[152:155], v[214:217], v[84:87]
	v_mfma_f32_16x16x32_bf16 v[72:75], v[160:163], v[214:217], v[72:75]
	v_mfma_f32_16x16x32_bf16 v[68:71], v[152:155], v[222:225], v[68:71]
	v_mfma_f32_16x16x32_bf16 v[64:67], v[160:163], v[222:225], v[64:67]
	s_setprio 0
	s_barrier
	s_add_i32 s55, s55, s38
	v_lshl_add_u64 v[206:207], s[22:23], 0, v[164:165]
	s_mov_b32 m0, s55
	ds_read_b128 v[174:177], v186 offset:16384
	ds_read_b128 v[190:193], v186 offset:17408
	ds_read_b128 v[194:197], v186 offset:18432
	ds_read_b128 v[198:201], v186 offset:19456
	ds_read_b128 v[202:205], v186 offset:20480
	ds_read_b128 v[214:217], v186 offset:21504
	ds_read_b128 v[218:221], v186 offset:22528
	ds_read_b128 v[222:225], v186 offset:23552
	global_load_lds_dwordx4 v[206:207], off
	s_add_i32 m0, s55, 0x2000
	s_add_u32 s60, s22, 0x4000
	v_lshl_add_u64 v[206:207], s[22:23], 0, v[168:169]
	s_addc_u32 s61, s23, 0
	s_add_i32 s55, s63, s38
	global_load_lds_dwordx4 v[206:207], off
	v_lshl_add_u64 v[206:207], s[60:61], 0, v[164:165]
	s_mov_b32 m0, s55
	v_lshl_add_u64 v[208:209], s[24:25], 0, v[166:167]
	global_load_lds_dwordx4 v[206:207], off
	v_lshl_add_u64 v[206:207], s[60:61], 0, v[168:169]
	s_add_i32 m0, s55, 0x2000
	s_nop 0
	global_load_lds_dwordx4 v[206:207], off
	v_lshl_add_u64 v[206:207], s[24:25], 0, v[2:3]
	s_mov_b32 m0, s39
	s_nop 0
	global_load_lds_dwordx4 v[206:207], off
	s_mov_b32 m0, s44
	s_nop 0
	global_load_lds_dwordx4 v[208:209], off
	s_waitcnt vmcnt(8)
	s_waitcnt lgkmcnt(0)
	s_barrier
	s_setprio 1
	s_waitcnt lgkmcnt(0)
	v_mfma_f32_16x16x32_bf16 v[60:63], v[132:135], v[174:177], 0
	v_mfma_f32_16x16x32_bf16 v[56:59], v[140:143], v[174:177], 0
	v_mfma_f32_16x16x32_bf16 v[44:47], v[132:135], v[194:197], 0
	v_mfma_f32_16x16x32_bf16 v[48:51], v[140:143], v[194:197], 0
	v_mfma_f32_16x16x32_bf16 v[28:31], v[132:135], v[202:205], 0
	v_mfma_f32_16x16x32_bf16 v[24:27], v[140:143], v[202:205], 0
	v_mfma_f32_16x16x32_bf16 v[112:115], v[132:135], v[218:221], 0
	v_mfma_f32_16x16x32_bf16 v[16:19], v[140:143], v[218:221], 0
	v_mfma_f32_16x16x32_bf16 v[60:63], v[136:139], v[190:193], v[60:63]
	v_mfma_f32_16x16x32_bf16 v[56:59], v[144:147], v[190:193], v[56:59]
	v_mfma_f32_16x16x32_bf16 v[44:47], v[136:139], v[198:201], v[44:47]
	v_mfma_f32_16x16x32_bf16 v[48:51], v[144:147], v[198:201], v[48:51]
	v_mfma_f32_16x16x32_bf16 v[28:31], v[136:139], v[214:217], v[28:31]
	v_mfma_f32_16x16x32_bf16 v[24:27], v[144:147], v[214:217], v[24:27]
	v_mfma_f32_16x16x32_bf16 v[112:115], v[136:139], v[222:225], v[112:115]
	v_mfma_f32_16x16x32_bf16 v[16:19], v[144:147], v[222:225], v[16:19]
	s_setprio 0
	s_setprio 1
	v_mfma_f32_16x16x32_bf16 v[52:55], v[148:151], v[174:177], 0
	v_mfma_f32_16x16x32_bf16 v[40:43], v[156:159], v[174:177], 0
	v_mfma_f32_16x16x32_bf16 v[36:39], v[148:151], v[194:197], 0
	v_mfma_f32_16x16x32_bf16 v[32:35], v[156:159], v[194:197], 0
	v_mfma_f32_16x16x32_bf16 v[20:23], v[148:151], v[202:205], 0
	v_mfma_f32_16x16x32_bf16 v[12:15], v[156:159], v[202:205], 0
	v_mfma_f32_16x16x32_bf16 v[4:7], v[148:151], v[218:221], 0
	v_mfma_f32_16x16x32_bf16 v[8:11], v[156:159], v[218:221], 0
	v_mfma_f32_16x16x32_bf16 v[52:55], v[152:155], v[190:193], v[52:55]
	v_mfma_f32_16x16x32_bf16 v[40:43], v[160:163], v[190:193], v[40:43]
	v_mfma_f32_16x16x32_bf16 v[36:39], v[152:155], v[198:201], v[36:39]
	v_mfma_f32_16x16x32_bf16 v[32:35], v[160:163], v[198:201], v[32:35]
	v_mfma_f32_16x16x32_bf16 v[20:23], v[152:155], v[214:217], v[20:23]
	v_mfma_f32_16x16x32_bf16 v[12:15], v[160:163], v[214:217], v[12:15]
	v_mfma_f32_16x16x32_bf16 v[4:7], v[152:155], v[222:225], v[4:7]
	v_mfma_f32_16x16x32_bf16 v[8:11], v[160:163], v[222:225], v[8:11]
	s_setprio 0
	s_barrier
	s_add_i32 s55, 0, 0x18000
	s_add_i32 s60, 0, 0x1c000
	v_add_u32_e32 v144, s55, v178
	v_add_u32_e32 v160, s60, v178
	ds_read_b128 v[132:135], v144
	ds_read_b128 v[136:139], v144 offset:1024
	ds_read_b128 v[140:143], v144 offset:2048
	ds_read_b128 v[144:147], v144 offset:3072
	ds_read_b128 v[148:151], v160
	ds_read_b128 v[152:155], v160 offset:1024
	ds_read_b128 v[156:159], v160 offset:2048
	ds_read_b128 v[160:163], v160 offset:3072
	s_add_u32 s24, s24, 0x80000
	s_addc_u32 s25, s25, 0
	s_mov_b32 m0, s45
	v_lshl_add_u64 v[210:211], s[24:25], 0, v[2:3]
	ds_read_b128 v[174:177], v186 offset:32768
	ds_read_b128 v[190:193], v186 offset:33792
	ds_read_b128 v[194:197], v186 offset:34816
	ds_read_b128 v[198:201], v186 offset:35840
	ds_read_b128 v[202:205], v186 offset:36864
	ds_read_b128 v[214:217], v186 offset:37888
	ds_read_b128 v[218:221], v186 offset:38912
	ds_read_b128 v[222:225], v186 offset:39936
	global_load_lds_dwordx4 v[210:211], off
	v_lshl_add_u64 v[210:211], s[24:25], 0, v[166:167]
	s_mov_b32 m0, s50
	s_nop 0
	global_load_lds_dwordx4 v[210:211], off
	s_waitcnt vmcnt(8)
	s_waitcnt lgkmcnt(0)
	s_barrier
	s_setprio 1
	s_waitcnt lgkmcnt(0)
	v_mfma_f32_16x16x32_bf16 v[128:131], v[132:135], v[174:177], v[128:131]
	v_mfma_f32_16x16x32_bf16 v[124:127], v[140:143], v[174:177], v[124:127]
	v_mfma_f32_16x16x32_bf16 v[108:111], v[132:135], v[194:197], v[108:111]
	v_mfma_f32_16x16x32_bf16 v[116:119], v[140:143], v[194:197], v[116:119]
	v_mfma_f32_16x16x32_bf16 v[92:95], v[132:135], v[202:205], v[92:95]
	v_mfma_f32_16x16x32_bf16 v[88:91], v[140:143], v[202:205], v[88:91]
	v_mfma_f32_16x16x32_bf16 v[76:79], v[132:135], v[218:221], v[76:79]
	v_mfma_f32_16x16x32_bf16 v[80:83], v[140:143], v[218:221], v[80:83]
	v_mfma_f32_16x16x32_bf16 v[128:131], v[136:139], v[190:193], v[128:131]
	v_mfma_f32_16x16x32_bf16 v[124:127], v[144:147], v[190:193], v[124:127]
	v_mfma_f32_16x16x32_bf16 v[108:111], v[136:139], v[198:201], v[108:111]
	v_mfma_f32_16x16x32_bf16 v[116:119], v[144:147], v[198:201], v[116:119]
	v_mfma_f32_16x16x32_bf16 v[92:95], v[136:139], v[214:217], v[92:95]
	v_mfma_f32_16x16x32_bf16 v[88:91], v[144:147], v[214:217], v[88:91]
	v_mfma_f32_16x16x32_bf16 v[76:79], v[136:139], v[222:225], v[76:79]
	v_mfma_f32_16x16x32_bf16 v[80:83], v[144:147], v[222:225], v[80:83]
	s_setprio 0
	s_setprio 1
	v_mfma_f32_16x16x32_bf16 v[120:123], v[148:151], v[174:177], v[120:123]
	v_mfma_f32_16x16x32_bf16 v[104:107], v[156:159], v[174:177], v[104:107]
	v_mfma_f32_16x16x32_bf16 v[100:103], v[148:151], v[194:197], v[100:103]
	v_mfma_f32_16x16x32_bf16 v[96:99], v[156:159], v[194:197], v[96:99]
	v_mfma_f32_16x16x32_bf16 v[84:87], v[148:151], v[202:205], v[84:87]
	v_mfma_f32_16x16x32_bf16 v[72:75], v[156:159], v[202:205], v[72:75]
	v_mfma_f32_16x16x32_bf16 v[68:71], v[148:151], v[218:221], v[68:71]
	v_mfma_f32_16x16x32_bf16 v[64:67], v[156:159], v[218:221], v[64:67]
	v_mfma_f32_16x16x32_bf16 v[120:123], v[152:155], v[190:193], v[120:123]
	v_mfma_f32_16x16x32_bf16 v[104:107], v[160:163], v[190:193], v[104:107]
	v_mfma_f32_16x16x32_bf16 v[100:103], v[152:155], v[198:201], v[100:103]
	v_mfma_f32_16x16x32_bf16 v[96:99], v[160:163], v[198:201], v[96:99]
	v_mfma_f32_16x16x32_bf16 v[84:87], v[152:155], v[214:217], v[84:87]
	v_mfma_f32_16x16x32_bf16 v[72:75], v[160:163], v[214:217], v[72:75]
	v_mfma_f32_16x16x32_bf16 v[68:71], v[152:155], v[222:225], v[68:71]
	v_mfma_f32_16x16x32_bf16 v[64:67], v[160:163], v[222:225], v[64:67]
	s_setprio 0
	s_barrier
	s_add_u32 s24, s22, 0x8000
	s_addc_u32 s25, s23, 0
	s_add_i32 s55, s55, s38
	v_lshl_add_u64 v[210:211], s[24:25], 0, v[164:165]
	s_mov_b32 m0, s55
	ds_read_b128 v[174:177], v186 offset:49152
	ds_read_b128 v[190:193], v186 offset:50176
	ds_read_b128 v[194:197], v186 offset:51200
	ds_read_b128 v[198:201], v186 offset:52224
	ds_read_b128 v[202:205], v186 offset:53248
	ds_read_b128 v[214:217], v186 offset:54272
	ds_read_b128 v[218:221], v186 offset:55296
	ds_read_b128 v[222:225], v186 offset:56320
	global_load_lds_dwordx4 v[210:211], off
	s_add_i32 m0, s55, 0x2000
	s_add_u32 s22, s22, 0xc000
	v_lshl_add_u64 v[210:211], s[24:25], 0, v[168:169]
	s_addc_u32 s23, s23, 0
	s_add_i32 s24, s60, s38
	global_load_lds_dwordx4 v[210:211], off
	v_lshl_add_u64 v[210:211], s[22:23], 0, v[164:165]
	s_mov_b32 m0, s24
	v_lshl_add_u64 v[206:207], v[206:207], 0, s[74:75]
	global_load_lds_dwordx4 v[210:211], off
	v_lshl_add_u64 v[210:211], s[22:23], 0, v[168:169]
	s_add_i32 m0, s24, 0x2000
	s_nop 0
	global_load_lds_dwordx4 v[210:211], off
	s_mov_b32 m0, s56
	s_nop 0
	global_load_lds_dwordx4 v[206:207], off
	v_lshl_add_u64 v[206:207], v[208:209], 0, s[74:75]
	s_mov_b32 m0, s57
	s_nop 0
	global_load_lds_dwordx4 v[206:207], off
	s_waitcnt vmcnt(8)
	s_waitcnt lgkmcnt(0)
	s_barrier
	s_setprio 1
	s_waitcnt lgkmcnt(0)
	v_mfma_f32_16x16x32_bf16 v[60:63], v[132:135], v[174:177], v[60:63]
	v_mfma_f32_16x16x32_bf16 v[56:59], v[140:143], v[174:177], v[56:59]
	v_mfma_f32_16x16x32_bf16 v[44:47], v[132:135], v[194:197], v[44:47]
	v_mfma_f32_16x16x32_bf16 v[48:51], v[140:143], v[194:197], v[48:51]
	v_mfma_f32_16x16x32_bf16 v[28:31], v[132:135], v[202:205], v[28:31]
	v_mfma_f32_16x16x32_bf16 v[24:27], v[140:143], v[202:205], v[24:27]
	v_mfma_f32_16x16x32_bf16 v[112:115], v[132:135], v[218:221], v[112:115]
	v_mfma_f32_16x16x32_bf16 v[16:19], v[140:143], v[218:221], v[16:19]
	v_mfma_f32_16x16x32_bf16 v[60:63], v[136:139], v[190:193], v[60:63]
	v_mfma_f32_16x16x32_bf16 v[56:59], v[144:147], v[190:193], v[56:59]
	v_mfma_f32_16x16x32_bf16 v[44:47], v[136:139], v[198:201], v[44:47]
	v_mfma_f32_16x16x32_bf16 v[48:51], v[144:147], v[198:201], v[48:51]
	v_mfma_f32_16x16x32_bf16 v[28:31], v[136:139], v[214:217], v[28:31]
	v_mfma_f32_16x16x32_bf16 v[24:27], v[144:147], v[214:217], v[24:27]
	v_mfma_f32_16x16x32_bf16 v[112:115], v[136:139], v[222:225], v[112:115]
	v_mfma_f32_16x16x32_bf16 v[16:19], v[144:147], v[222:225], v[16:19]
	s_setprio 0
	s_setprio 1
	v_mfma_f32_16x16x32_bf16 v[52:55], v[148:151], v[174:177], v[52:55]
	v_mfma_f32_16x16x32_bf16 v[40:43], v[156:159], v[174:177], v[40:43]
	v_mfma_f32_16x16x32_bf16 v[36:39], v[148:151], v[194:197], v[36:39]
	v_mfma_f32_16x16x32_bf16 v[32:35], v[156:159], v[194:197], v[32:35]
	v_mfma_f32_16x16x32_bf16 v[20:23], v[148:151], v[202:205], v[20:23]
	v_mfma_f32_16x16x32_bf16 v[12:15], v[156:159], v[202:205], v[12:15]
	v_mfma_f32_16x16x32_bf16 v[4:7], v[148:151], v[218:221], v[4:7]
	v_mfma_f32_16x16x32_bf16 v[8:11], v[156:159], v[218:221], v[8:11]
	v_mfma_f32_16x16x32_bf16 v[52:55], v[152:155], v[190:193], v[52:55]
	v_mfma_f32_16x16x32_bf16 v[40:43], v[160:163], v[190:193], v[40:43]
	v_mfma_f32_16x16x32_bf16 v[36:39], v[152:155], v[198:201], v[36:39]
	v_mfma_f32_16x16x32_bf16 v[32:35], v[160:163], v[198:201], v[32:35]
	v_mfma_f32_16x16x32_bf16 v[20:23], v[152:155], v[214:217], v[20:23]
	v_mfma_f32_16x16x32_bf16 v[12:15], v[160:163], v[214:217], v[12:15]
	v_mfma_f32_16x16x32_bf16 v[4:7], v[152:155], v[222:225], v[4:7]
	v_mfma_f32_16x16x32_bf16 v[8:11], v[160:163], v[222:225], v[8:11]
	s_setprio 0
	s_barrier
	s_add_i32 s54, s54, 2
	s_add_u32 s29, s29, 0x10000
	s_addc_u32 s49, s49, 0
	s_add_u32 s20, s20, 0x100
	s_addc_u32 s21, s21, 0
	s_cmp_gt_u32 s54, 29

.LBB0_743:
	s_ashr_i32 s7, s6, 31
	s_lshl_b64 s[12:13], s[6:7], 20
	s_add_u32 s12, s25, s12
	s_addc_u32 s13, s26, s13
	s_and_b64 s[14:15], s[8:9], exec
	s_cselect_b32 s7, s13, s19
	s_cselect_b32 s45, s12, s18
	s_ashr_i32 s11, s10, 31
	s_lshl_b64 s[14:15], s[10:11], 20
	s_add_u32 s14, s27, s14
	s_addc_u32 s15, s28, s15
	s_and_b64 s[20:21], s[8:9], exec
	s_cselect_b32 s11, s15, s17
	s_cselect_b32 s46, s14, s16
	s_add_u32 s47, s16, 0x10000
	s_addc_u32 s48, s17, 0
	s_add_u32 s16, s18, 0x80080
	s_addc_u32 s17, s19, 0
	s_mov_b32 s49, -2
	s_add_u32 s18, s16, 0xfff80080
	s_addc_u32 s19, s17, -1
	s_add_i32 s50, 0, 0x10000
	s_cmp_eq_u32 s49, 28
	s_cselect_b32 s21, s7, s19
	s_cselect_b32 s20, s45, s18
	s_cselect_b32 s19, s11, s48
	s_cselect_b32 s18, s46, s47
	s_add_i32 s52, 0, 0x14000
	v_add_u32_e32 v168, s50, v158
	v_add_u32_e32 v184, s52, v158
	ds_read_b128 v[154:157], v168
	ds_read_b128 v[160:163], v168 offset:1024
	ds_read_b128 v[164:167], v168 offset:2048
	ds_read_b128 v[168:171], v168 offset:3072
	ds_read_b128 v[172:175], v184
	ds_read_b128 v[176:179], v184 offset:1024
	ds_read_b128 v[180:183], v184 offset:2048
	ds_read_b128 v[184:187], v184 offset:3072
	v_lshl_add_u64 v[208:209], s[16:17], 0, v[150:151]
	s_add_i32 m0, s30, 0xc000
	ds_read_b128 v[188:191], v159
	ds_read_b128 v[192:195], v159 offset:1024
	ds_read_b128 v[196:199], v159 offset:2048
	ds_read_b128 v[200:203], v159 offset:3072
	ds_read_b128 v[204:207], v159 offset:4096
	ds_read_b128 v[214:217], v159 offset:5120
	ds_read_b128 v[218:221], v159 offset:6144
	ds_read_b128 v[222:225], v159 offset:7168
	global_load_lds_dwordx4 v[208:209], off
	v_lshl_add_u64 v[208:209], s[16:17], 0, v[152:153]
	s_add_i32 m0, s30, 0xe000
	s_nop 0
	global_load_lds_dwordx4 v[208:209], off
	s_waitcnt vmcnt(8)
	s_waitcnt lgkmcnt(0)
	s_barrier
	s_setprio 1
	s_waitcnt lgkmcnt(0)
	v_mfma_f32_16x16x32_bf16 v[128:131], v[154:157], v[188:191], 0
	v_mfma_f32_16x16x32_bf16 v[120:123], v[164:167], v[188:191], 0
	v_mfma_f32_16x16x32_bf16 v[112:115], v[154:157], v[196:199], 0
	v_mfma_f32_16x16x32_bf16 v[104:107], v[164:167], v[196:199], 0
	v_mfma_f32_16x16x32_bf16 v[96:99], v[154:157], v[204:207], 0
	v_mfma_f32_16x16x32_bf16 v[88:91], v[164:167], v[204:207], 0
	v_mfma_f32_16x16x32_bf16 v[80:83], v[154:157], v[218:221], 0
	v_mfma_f32_16x16x32_bf16 v[72:75], v[164:167], v[218:221], 0
	v_mfma_f32_16x16x32_bf16 v[128:131], v[160:163], v[192:195], v[128:131]
	v_mfma_f32_16x16x32_bf16 v[120:123], v[168:171], v[192:195], v[120:123]
	v_mfma_f32_16x16x32_bf16 v[112:115], v[160:163], v[200:203], v[112:115]
	v_mfma_f32_16x16x32_bf16 v[104:107], v[168:171], v[200:203], v[104:107]
	v_mfma_f32_16x16x32_bf16 v[96:99], v[160:163], v[214:217], v[96:99]
	v_mfma_f32_16x16x32_bf16 v[88:91], v[168:171], v[214:217], v[88:91]
	v_mfma_f32_16x16x32_bf16 v[80:83], v[160:163], v[222:225], v[80:83]
	v_mfma_f32_16x16x32_bf16 v[72:75], v[168:171], v[222:225], v[72:75]
	s_setprio 0
	s_setprio 1
	v_mfma_f32_16x16x32_bf16 v[124:127], v[172:175], v[188:191], 0
	v_mfma_f32_16x16x32_bf16 v[116:119], v[180:183], v[188:191], 0
	v_mfma_f32_16x16x32_bf16 v[108:111], v[172:175], v[196:199], 0
	v_mfma_f32_16x16x32_bf16 v[100:103], v[180:183], v[196:199], 0
	v_mfma_f32_16x16x32_bf16 v[92:95], v[172:175], v[204:207], 0
	v_mfma_f32_16x16x32_bf16 v[84:87], v[180:183], v[204:207], 0
	v_mfma_f32_16x16x32_bf16 v[76:79], v[172:175], v[218:221], 0
	v_mfma_f32_16x16x32_bf16 v[68:71], v[180:183], v[218:221], 0
	v_mfma_f32_16x16x32_bf16 v[124:127], v[176:179], v[192:195], v[124:127]
	v_mfma_f32_16x16x32_bf16 v[116:119], v[184:187], v[192:195], v[116:119]
	v_mfma_f32_16x16x32_bf16 v[108:111], v[176:179], v[200:203], v[108:111]
	v_mfma_f32_16x16x32_bf16 v[100:103], v[184:187], v[200:203], v[100:103]
	v_mfma_f32_16x16x32_bf16 v[92:95], v[176:179], v[214:217], v[92:95]
	v_mfma_f32_16x16x32_bf16 v[84:87], v[184:187], v[214:217], v[84:87]
	v_mfma_f32_16x16x32_bf16 v[76:79], v[176:179], v[222:225], v[76:79]
	v_mfma_f32_16x16x32_bf16 v[68:71], v[184:187], v[222:225], v[68:71]
	s_setprio 0
	s_barrier
	s_add_i32 s50, s50, s29
	v_lshl_add_u64 v[208:209], s[18:19], 0, v[136:137]
	s_mov_b32 m0, s50
	ds_read_b128 v[188:191], v159 offset:16384
	ds_read_b128 v[192:195], v159 offset:17408
	ds_read_b128 v[196:199], v159 offset:18432
	ds_read_b128 v[200:203], v159 offset:19456
	ds_read_b128 v[204:207], v159 offset:20480
	ds_read_b128 v[214:217], v159 offset:21504
	ds_read_b128 v[218:221], v159 offset:22528
	ds_read_b128 v[222:225], v159 offset:23552
	global_load_lds_dwordx4 v[208:209], off
	s_add_i32 m0, s50, 0x2000
	s_add_u32 s50, s18, 0x4000
	v_lshl_add_u64 v[208:209], s[18:19], 0, v[132:133]
	s_addc_u32 s51, s19, 0
	s_add_i32 s52, s52, s29
	global_load_lds_dwordx4 v[208:209], off
	v_lshl_add_u64 v[208:209], s[50:51], 0, v[136:137]
	s_mov_b32 m0, s52
	v_lshl_add_u64 v[210:211], s[20:21], 0, v[134:135]
	global_load_lds_dwordx4 v[208:209], off
	v_lshl_add_u64 v[208:209], s[50:51], 0, v[132:133]
	s_add_i32 m0, s52, 0x2000
	s_nop 0
	global_load_lds_dwordx4 v[208:209], off
	v_lshl_add_u64 v[208:209], s[20:21], 0, v[138:139]
	s_mov_b32 m0, s30
	s_nop 0
	global_load_lds_dwordx4 v[208:209], off
	s_mov_b32 m0, s31
	s_nop 0
	global_load_lds_dwordx4 v[210:211], off
	s_waitcnt vmcnt(8)
	s_waitcnt lgkmcnt(0)
	s_barrier
	s_setprio 1
	s_waitcnt lgkmcnt(0)
	v_mfma_f32_16x16x32_bf16 v[64:67], v[154:157], v[188:191], 0
	v_mfma_f32_16x16x32_bf16 v[56:59], v[164:167], v[188:191], 0
	v_mfma_f32_16x16x32_bf16 v[48:51], v[154:157], v[196:199], 0
	v_mfma_f32_16x16x32_bf16 v[40:43], v[164:167], v[196:199], 0
	v_mfma_f32_16x16x32_bf16 v[32:35], v[154:157], v[204:207], 0
	v_mfma_f32_16x16x32_bf16 v[24:27], v[164:167], v[204:207], 0
	v_mfma_f32_16x16x32_bf16 v[16:19], v[154:157], v[218:221], 0
	v_mfma_f32_16x16x32_bf16 v[8:11], v[164:167], v[218:221], 0
	v_mfma_f32_16x16x32_bf16 v[64:67], v[160:163], v[192:195], v[64:67]
	v_mfma_f32_16x16x32_bf16 v[56:59], v[168:171], v[192:195], v[56:59]
	v_mfma_f32_16x16x32_bf16 v[48:51], v[160:163], v[200:203], v[48:51]
	v_mfma_f32_16x16x32_bf16 v[40:43], v[168:171], v[200:203], v[40:43]
	v_mfma_f32_16x16x32_bf16 v[32:35], v[160:163], v[214:217], v[32:35]
	v_mfma_f32_16x16x32_bf16 v[24:27], v[168:171], v[214:217], v[24:27]
	v_mfma_f32_16x16x32_bf16 v[16:19], v[160:163], v[222:225], v[16:19]
	v_mfma_f32_16x16x32_bf16 v[8:11], v[168:171], v[222:225], v[8:11]
	s_setprio 0
	s_setprio 1
	v_mfma_f32_16x16x32_bf16 v[60:63], v[172:175], v[188:191], 0
	v_mfma_f32_16x16x32_bf16 v[52:55], v[180:183], v[188:191], 0
	v_mfma_f32_16x16x32_bf16 v[44:47], v[172:175], v[196:199], 0
	v_mfma_f32_16x16x32_bf16 v[36:39], v[180:183], v[196:199], 0
	v_mfma_f32_16x16x32_bf16 v[28:31], v[172:175], v[204:207], 0
	v_mfma_f32_16x16x32_bf16 v[20:23], v[180:183], v[204:207], 0
	v_mfma_f32_16x16x32_bf16 v[12:15], v[172:175], v[218:221], 0
	v_mfma_f32_16x16x32_bf16 v[4:7], v[180:183], v[218:221], 0
	v_mfma_f32_16x16x32_bf16 v[60:63], v[176:179], v[192:195], v[60:63]
	v_mfma_f32_16x16x32_bf16 v[52:55], v[184:187], v[192:195], v[52:55]
	v_mfma_f32_16x16x32_bf16 v[44:47], v[176:179], v[200:203], v[44:47]
	v_mfma_f32_16x16x32_bf16 v[36:39], v[184:187], v[200:203], v[36:39]
	v_mfma_f32_16x16x32_bf16 v[28:31], v[176:179], v[214:217], v[28:31]
	v_mfma_f32_16x16x32_bf16 v[20:23], v[184:187], v[214:217], v[20:23]
	v_mfma_f32_16x16x32_bf16 v[12:15], v[176:179], v[222:225], v[12:15]
	v_mfma_f32_16x16x32_bf16 v[4:7], v[184:187], v[222:225], v[4:7]
	s_setprio 0
	s_barrier
	s_add_i32 s50, 0, 0x18000
	s_add_i32 s51, 0, 0x1c000
	v_add_u32_e32 v168, s50, v158
	v_add_u32_e32 v184, s51, v158
	ds_read_b128 v[154:157], v168
	ds_read_b128 v[160:163], v168 offset:1024
	ds_read_b128 v[164:167], v168 offset:2048
	ds_read_b128 v[168:171], v168 offset:3072
	ds_read_b128 v[172:175], v184
	ds_read_b128 v[176:179], v184 offset:1024
	ds_read_b128 v[180:183], v184 offset:2048
	ds_read_b128 v[184:187], v184 offset:3072
	s_add_u32 s20, s20, 0x80000
	s_addc_u32 s21, s21, 0
	s_mov_b32 m0, s34
	v_lshl_add_u64 v[226:227], s[20:21], 0, v[138:139]
	ds_read_b128 v[188:191], v159 offset:32768
	ds_read_b128 v[192:195], v159 offset:33792
	ds_read_b128 v[196:199], v159 offset:34816
	ds_read_b128 v[200:203], v159 offset:35840
	ds_read_b128 v[204:207], v159 offset:36864
	ds_read_b128 v[214:217], v159 offset:37888
	ds_read_b128 v[218:221], v159 offset:38912
	ds_read_b128 v[222:225], v159 offset:39936
	global_load_lds_dwordx4 v[226:227], off
	v_lshl_add_u64 v[226:227], s[20:21], 0, v[134:135]
	s_mov_b32 m0, s35
	s_nop 0
	global_load_lds_dwordx4 v[226:227], off
	s_waitcnt vmcnt(8)
	s_waitcnt lgkmcnt(0)
	s_barrier
	s_setprio 1
	s_waitcnt lgkmcnt(0)
	v_mfma_f32_16x16x32_bf16 v[128:131], v[154:157], v[188:191], v[128:131]
	v_mfma_f32_16x16x32_bf16 v[120:123], v[164:167], v[188:191], v[120:123]
	v_mfma_f32_16x16x32_bf16 v[112:115], v[154:157], v[196:199], v[112:115]
	v_mfma_f32_16x16x32_bf16 v[104:107], v[164:167], v[196:199], v[104:107]
	v_mfma_f32_16x16x32_bf16 v[96:99], v[154:157], v[204:207], v[96:99]
	v_mfma_f32_16x16x32_bf16 v[88:91], v[164:167], v[204:207], v[88:91]
	v_mfma_f32_16x16x32_bf16 v[80:83], v[154:157], v[218:221], v[80:83]
	v_mfma_f32_16x16x32_bf16 v[72:75], v[164:167], v[218:221], v[72:75]
	v_mfma_f32_16x16x32_bf16 v[128:131], v[160:163], v[192:195], v[128:131]
	v_mfma_f32_16x16x32_bf16 v[120:123], v[168:171], v[192:195], v[120:123]
	v_mfma_f32_16x16x32_bf16 v[112:115], v[160:163], v[200:203], v[112:115]
	v_mfma_f32_16x16x32_bf16 v[104:107], v[168:171], v[200:203], v[104:107]
	v_mfma_f32_16x16x32_bf16 v[96:99], v[160:163], v[214:217], v[96:99]
	v_mfma_f32_16x16x32_bf16 v[88:91], v[168:171], v[214:217], v[88:91]
	v_mfma_f32_16x16x32_bf16 v[80:83], v[160:163], v[222:225], v[80:83]
	v_mfma_f32_16x16x32_bf16 v[72:75], v[168:171], v[222:225], v[72:75]
	s_setprio 0
	s_setprio 1
	v_mfma_f32_16x16x32_bf16 v[124:127], v[172:175], v[188:191], v[124:127]
	v_mfma_f32_16x16x32_bf16 v[116:119], v[180:183], v[188:191], v[116:119]
	v_mfma_f32_16x16x32_bf16 v[108:111], v[172:175], v[196:199], v[108:111]
	v_mfma_f32_16x16x32_bf16 v[100:103], v[180:183], v[196:199], v[100:103]
	v_mfma_f32_16x16x32_bf16 v[92:95], v[172:175], v[204:207], v[92:95]
	v_mfma_f32_16x16x32_bf16 v[84:87], v[180:183], v[204:207], v[84:87]
	v_mfma_f32_16x16x32_bf16 v[76:79], v[172:175], v[218:221], v[76:79]
	v_mfma_f32_16x16x32_bf16 v[68:71], v[180:183], v[218:221], v[68:71]
	v_mfma_f32_16x16x32_bf16 v[124:127], v[176:179], v[192:195], v[124:127]
	v_mfma_f32_16x16x32_bf16 v[116:119], v[184:187], v[192:195], v[116:119]
	v_mfma_f32_16x16x32_bf16 v[108:111], v[176:179], v[200:203], v[108:111]
	v_mfma_f32_16x16x32_bf16 v[100:103], v[184:187], v[200:203], v[100:103]
	v_mfma_f32_16x16x32_bf16 v[92:95], v[176:179], v[214:217], v[92:95]
	v_mfma_f32_16x16x32_bf16 v[84:87], v[184:187], v[214:217], v[84:87]
	v_mfma_f32_16x16x32_bf16 v[76:79], v[176:179], v[222:225], v[76:79]
	v_mfma_f32_16x16x32_bf16 v[68:71], v[184:187], v[222:225], v[68:71]
	s_setprio 0
	s_barrier
	s_add_u32 s20, s18, 0x8000
	s_addc_u32 s21, s19, 0
	s_add_i32 s50, s50, s29
	v_lshl_add_u64 v[226:227], s[20:21], 0, v[136:137]
	s_mov_b32 m0, s50
	ds_read_b128 v[188:191], v159 offset:49152
	ds_read_b128 v[192:195], v159 offset:50176
	ds_read_b128 v[196:199], v159 offset:51200
	ds_read_b128 v[200:203], v159 offset:52224
	ds_read_b128 v[204:207], v159 offset:53248
	ds_read_b128 v[214:217], v159 offset:54272
	ds_read_b128 v[218:221], v159 offset:55296
	ds_read_b128 v[222:225], v159 offset:56320
	global_load_lds_dwordx4 v[226:227], off
	s_add_i32 m0, s50, 0x2000
	s_add_u32 s18, s18, 0xc000
	v_lshl_add_u64 v[226:227], s[20:21], 0, v[132:133]
	s_addc_u32 s19, s19, 0
	s_add_i32 s20, s51, s29
	global_load_lds_dwordx4 v[226:227], off
	v_lshl_add_u64 v[226:227], s[18:19], 0, v[136:137]
	s_mov_b32 m0, s20
	v_lshl_add_u64 v[208:209], v[208:209], 0, s[74:75]
	global_load_lds_dwordx4 v[226:227], off
	v_lshl_add_u64 v[226:227], s[18:19], 0, v[132:133]
	s_add_i32 m0, s20, 0x2000
	s_nop 0
	global_load_lds_dwordx4 v[226:227], off
	s_mov_b32 m0, s39
	s_nop 0
	global_load_lds_dwordx4 v[208:209], off
	v_lshl_add_u64 v[208:209], v[210:211], 0, s[74:75]
	s_mov_b32 m0, s40
	s_nop 0
	global_load_lds_dwordx4 v[208:209], off
	s_waitcnt vmcnt(8)
	s_waitcnt lgkmcnt(0)
	s_barrier
	s_setprio 1
	s_waitcnt lgkmcnt(0)
	v_mfma_f32_16x16x32_bf16 v[64:67], v[154:157], v[188:191], v[64:67]
	v_mfma_f32_16x16x32_bf16 v[56:59], v[164:167], v[188:191], v[56:59]
	v_mfma_f32_16x16x32_bf16 v[48:51], v[154:157], v[196:199], v[48:51]
	v_mfma_f32_16x16x32_bf16 v[40:43], v[164:167], v[196:199], v[40:43]
	v_mfma_f32_16x16x32_bf16 v[32:35], v[154:157], v[204:207], v[32:35]
	v_mfma_f32_16x16x32_bf16 v[24:27], v[164:167], v[204:207], v[24:27]
	v_mfma_f32_16x16x32_bf16 v[16:19], v[154:157], v[218:221], v[16:19]
	v_mfma_f32_16x16x32_bf16 v[8:11], v[164:167], v[218:221], v[8:11]
	v_mfma_f32_16x16x32_bf16 v[64:67], v[160:163], v[192:195], v[64:67]
	v_mfma_f32_16x16x32_bf16 v[56:59], v[168:171], v[192:195], v[56:59]
	v_mfma_f32_16x16x32_bf16 v[48:51], v[160:163], v[200:203], v[48:51]
	v_mfma_f32_16x16x32_bf16 v[40:43], v[168:171], v[200:203], v[40:43]
	v_mfma_f32_16x16x32_bf16 v[32:35], v[160:163], v[214:217], v[32:35]
	v_mfma_f32_16x16x32_bf16 v[24:27], v[168:171], v[214:217], v[24:27]
	v_mfma_f32_16x16x32_bf16 v[16:19], v[160:163], v[222:225], v[16:19]
	v_mfma_f32_16x16x32_bf16 v[8:11], v[168:171], v[222:225], v[8:11]
	s_setprio 0
	s_setprio 1
	v_mfma_f32_16x16x32_bf16 v[60:63], v[172:175], v[188:191], v[60:63]
	v_mfma_f32_16x16x32_bf16 v[52:55], v[180:183], v[188:191], v[52:55]
	v_mfma_f32_16x16x32_bf16 v[44:47], v[172:175], v[196:199], v[44:47]
	v_mfma_f32_16x16x32_bf16 v[36:39], v[180:183], v[196:199], v[36:39]
	v_mfma_f32_16x16x32_bf16 v[28:31], v[172:175], v[204:207], v[28:31]
	v_mfma_f32_16x16x32_bf16 v[20:23], v[180:183], v[204:207], v[20:23]
	v_mfma_f32_16x16x32_bf16 v[12:15], v[172:175], v[218:221], v[12:15]
	v_mfma_f32_16x16x32_bf16 v[4:7], v[180:183], v[218:221], v[4:7]
	v_mfma_f32_16x16x32_bf16 v[60:63], v[176:179], v[192:195], v[60:63]
	v_mfma_f32_16x16x32_bf16 v[52:55], v[184:187], v[192:195], v[52:55]
	v_mfma_f32_16x16x32_bf16 v[44:47], v[176:179], v[200:203], v[44:47]
	v_mfma_f32_16x16x32_bf16 v[36:39], v[184:187], v[200:203], v[36:39]
	v_mfma_f32_16x16x32_bf16 v[28:31], v[176:179], v[214:217], v[28:31]
	v_mfma_f32_16x16x32_bf16 v[20:23], v[184:187], v[214:217], v[20:23]
	v_mfma_f32_16x16x32_bf16 v[12:15], v[176:179], v[222:225], v[12:15]
	v_mfma_f32_16x16x32_bf16 v[4:7], v[184:187], v[222:225], v[4:7]
	s_setprio 0
	s_barrier
	s_add_i32 s49, s49, 2
	s_add_u32 s47, s47, 0x10000
	s_addc_u32 s48, s48, 0
	s_add_u32 s16, s16, 0x100
	s_addc_u32 s17, s17, 0
	s_cmp_gt_u32 s49, 29

.LBB0_809:
	s_add_u32 s18, s22, 0xc000
	s_addc_u32 s19, s23, 0
	s_add_u32 s6, s20, 0x10000
	s_addc_u32 s7, s21, 0
	s_mov_b32 s26, -2
	s_add_u32 s20, s18, 0x4000
	s_addc_u32 s21, s19, 0
	s_cmpk_eq_i32 s26, 0x54
	s_cselect_b32 s24, s34, s20
	s_cselect_b32 s25, s35, s21
	s_cselect_b32 s22, s38, s6
	s_cselect_b32 s23, s39, s7
	s_add_u32 s20, s24, 0x8000
	s_addc_u32 s21, s25, 0
	s_add_i32 s27, 0, 0x10000
	s_add_i32 s45, 0, 0x14000
	v_add_u32_e32 v144, s27, v180
	v_add_u32_e32 v166, s45, v180
	ds_read_b128 v[132:135], v144
	ds_read_b128 v[136:139], v144 offset:1024
	ds_read_b128 v[140:143], v144 offset:2048
	ds_read_b128 v[144:147], v144 offset:3072
	ds_read_b128 v[148:151], v166
	ds_read_b128 v[152:155], v166 offset:1024
	ds_read_b128 v[156:159], v166 offset:2048
	ds_read_b128 v[166:169], v166 offset:3072
	v_lshl_add_u64 v[178:179], s[18:19], 0, v[162:163]
	s_add_i32 m0, s79, 0xc000
	ds_read_b128 v[170:173], v188
	ds_read_b128 v[174:177], v188 offset:1024
	ds_read_b128 v[192:195], v188 offset:2048
	ds_read_b128 v[196:199], v188 offset:3072
	ds_read_b128 v[200:203], v188 offset:4096
	ds_read_b128 v[204:207], v188 offset:5120
	ds_read_b128 v[214:217], v188 offset:6144
	ds_read_b128 v[218:221], v188 offset:7168
	global_load_lds_dwordx4 v[178:179], off
	v_lshl_add_u64 v[178:179], s[18:19], 0, v[164:165]
	s_add_i32 m0, s79, 0xe000
	s_nop 0
	global_load_lds_dwordx4 v[178:179], off
	s_waitcnt vmcnt(8)
	s_waitcnt lgkmcnt(0)
	s_barrier
	s_setprio 1
	s_waitcnt lgkmcnt(0)
	v_mfma_f32_16x16x32_bf16 v[128:131], v[132:135], v[170:173], 0
	v_mfma_f32_16x16x32_bf16 v[124:127], v[140:143], v[170:173], 0
	v_mfma_f32_16x16x32_bf16 v[116:119], v[132:135], v[192:195], 0
	v_mfma_f32_16x16x32_bf16 v[112:115], v[140:143], v[192:195], 0
	v_mfma_f32_16x16x32_bf16 v[96:99], v[132:135], v[200:203], 0
	v_mfma_f32_16x16x32_bf16 v[92:95], v[140:143], v[200:203], 0
	v_mfma_f32_16x16x32_bf16 v[80:83], v[132:135], v[214:217], 0
	v_mfma_f32_16x16x32_bf16 v[84:87], v[140:143], v[214:217], 0
	v_mfma_f32_16x16x32_bf16 v[128:131], v[136:139], v[174:177], v[128:131]
	v_mfma_f32_16x16x32_bf16 v[124:127], v[144:147], v[174:177], v[124:127]
	v_mfma_f32_16x16x32_bf16 v[116:119], v[136:139], v[196:199], v[116:119]
	v_mfma_f32_16x16x32_bf16 v[112:115], v[144:147], v[196:199], v[112:115]
	v_mfma_f32_16x16x32_bf16 v[96:99], v[136:139], v[204:207], v[96:99]
	v_mfma_f32_16x16x32_bf16 v[92:95], v[144:147], v[204:207], v[92:95]
	v_mfma_f32_16x16x32_bf16 v[80:83], v[136:139], v[218:221], v[80:83]
	v_mfma_f32_16x16x32_bf16 v[84:87], v[144:147], v[218:221], v[84:87]
	s_setprio 0
	s_setprio 1
	v_mfma_f32_16x16x32_bf16 v[120:123], v[148:151], v[170:173], 0
	v_mfma_f32_16x16x32_bf16 v[108:111], v[156:159], v[170:173], 0
	v_mfma_f32_16x16x32_bf16 v[104:107], v[148:151], v[192:195], 0
	v_mfma_f32_16x16x32_bf16 v[100:103], v[156:159], v[192:195], 0
	v_mfma_f32_16x16x32_bf16 v[88:91], v[148:151], v[200:203], 0
	v_mfma_f32_16x16x32_bf16 v[72:75], v[156:159], v[200:203], 0
	v_mfma_f32_16x16x32_bf16 v[68:71], v[148:151], v[214:217], 0
	v_mfma_f32_16x16x32_bf16 v[64:67], v[156:159], v[214:217], 0
	v_mfma_f32_16x16x32_bf16 v[120:123], v[152:155], v[174:177], v[120:123]
	v_mfma_f32_16x16x32_bf16 v[108:111], v[166:169], v[174:177], v[108:111]
	v_mfma_f32_16x16x32_bf16 v[104:107], v[152:155], v[196:199], v[104:107]
	v_mfma_f32_16x16x32_bf16 v[100:103], v[166:169], v[196:199], v[100:103]
	v_mfma_f32_16x16x32_bf16 v[88:91], v[152:155], v[204:207], v[88:91]
	v_mfma_f32_16x16x32_bf16 v[72:75], v[166:169], v[204:207], v[72:75]
	v_mfma_f32_16x16x32_bf16 v[68:71], v[152:155], v[218:221], v[68:71]
	v_mfma_f32_16x16x32_bf16 v[64:67], v[166:169], v[218:221], v[64:67]
	s_setprio 0
	s_barrier
	s_add_i32 s27, s27, s78
	v_lshl_add_u64 v[178:179], s[22:23], 0, v[2:3]
	s_mov_b32 m0, s27
	ds_read_b128 v[170:173], v188 offset:16384
	ds_read_b128 v[174:177], v188 offset:17408
	ds_read_b128 v[192:195], v188 offset:18432
	ds_read_b128 v[196:199], v188 offset:19456
	ds_read_b128 v[200:203], v188 offset:20480
	ds_read_b128 v[204:207], v188 offset:21504
	ds_read_b128 v[214:217], v188 offset:22528
	ds_read_b128 v[218:221], v188 offset:23552
	global_load_lds_dwordx4 v[178:179], off
	s_add_i32 m0, s27, 0x2000
	s_add_u32 s50, s22, 0x4000
	v_lshl_add_u64 v[178:179], s[22:23], 0, v[160:161]
	s_addc_u32 s51, s23, 0
	s_add_i32 s27, s45, s78
	global_load_lds_dwordx4 v[178:179], off
	v_lshl_add_u64 v[178:179], s[50:51], 0, v[2:3]
	s_mov_b32 m0, s27
	s_nop 0
	global_load_lds_dwordx4 v[178:179], off
	v_lshl_add_u64 v[178:179], s[50:51], 0, v[160:161]
	s_add_i32 m0, s27, 0x2000
	s_nop 0
	global_load_lds_dwordx4 v[178:179], off
	v_lshl_add_u64 v[178:179], s[24:25], 0, v[2:3]
	s_mov_b32 m0, s79
	s_nop 0
	global_load_lds_dwordx4 v[178:179], off
	v_lshl_add_u64 v[178:179], s[24:25], 0, v[160:161]
	s_mov_b32 m0, s40
	s_nop 0
	global_load_lds_dwordx4 v[178:179], off
	s_waitcnt vmcnt(8)
	s_waitcnt lgkmcnt(0)
	s_barrier
	s_setprio 1
	s_waitcnt lgkmcnt(0)
	v_mfma_f32_16x16x32_bf16 v[60:63], v[132:135], v[170:173], 0
	v_mfma_f32_16x16x32_bf16 v[56:59], v[140:143], v[170:173], 0
	v_mfma_f32_16x16x32_bf16 v[44:47], v[132:135], v[192:195], 0
	v_mfma_f32_16x16x32_bf16 v[48:51], v[140:143], v[192:195], 0
	v_mfma_f32_16x16x32_bf16 v[28:31], v[132:135], v[200:203], 0
	v_mfma_f32_16x16x32_bf16 v[24:27], v[140:143], v[200:203], 0
	v_mfma_f32_16x16x32_bf16 v[76:79], v[132:135], v[214:217], 0
	v_mfma_f32_16x16x32_bf16 v[16:19], v[140:143], v[214:217], 0
	v_mfma_f32_16x16x32_bf16 v[60:63], v[136:139], v[174:177], v[60:63]
	v_mfma_f32_16x16x32_bf16 v[56:59], v[144:147], v[174:177], v[56:59]
	v_mfma_f32_16x16x32_bf16 v[44:47], v[136:139], v[196:199], v[44:47]
	v_mfma_f32_16x16x32_bf16 v[48:51], v[144:147], v[196:199], v[48:51]
	v_mfma_f32_16x16x32_bf16 v[28:31], v[136:139], v[204:207], v[28:31]
	v_mfma_f32_16x16x32_bf16 v[24:27], v[144:147], v[204:207], v[24:27]
	v_mfma_f32_16x16x32_bf16 v[76:79], v[136:139], v[218:221], v[76:79]
	v_mfma_f32_16x16x32_bf16 v[16:19], v[144:147], v[218:221], v[16:19]
	s_setprio 0
	s_setprio 1
	v_mfma_f32_16x16x32_bf16 v[52:55], v[148:151], v[170:173], 0
	v_mfma_f32_16x16x32_bf16 v[40:43], v[156:159], v[170:173], 0
	v_mfma_f32_16x16x32_bf16 v[36:39], v[148:151], v[192:195], 0
	v_mfma_f32_16x16x32_bf16 v[32:35], v[156:159], v[192:195], 0
	v_mfma_f32_16x16x32_bf16 v[20:23], v[148:151], v[200:203], 0
	v_mfma_f32_16x16x32_bf16 v[12:15], v[156:159], v[200:203], 0
	v_mfma_f32_16x16x32_bf16 v[4:7], v[148:151], v[214:217], 0
	v_mfma_f32_16x16x32_bf16 v[8:11], v[156:159], v[214:217], 0
	v_mfma_f32_16x16x32_bf16 v[52:55], v[152:155], v[174:177], v[52:55]
	v_mfma_f32_16x16x32_bf16 v[40:43], v[166:169], v[174:177], v[40:43]
	v_mfma_f32_16x16x32_bf16 v[36:39], v[152:155], v[196:199], v[36:39]
	v_mfma_f32_16x16x32_bf16 v[32:35], v[166:169], v[196:199], v[32:35]
	v_mfma_f32_16x16x32_bf16 v[20:23], v[152:155], v[204:207], v[20:23]
	v_mfma_f32_16x16x32_bf16 v[12:15], v[166:169], v[204:207], v[12:15]
	v_mfma_f32_16x16x32_bf16 v[4:7], v[152:155], v[218:221], v[4:7]
	v_mfma_f32_16x16x32_bf16 v[8:11], v[166:169], v[218:221], v[8:11]
	s_setprio 0
	s_barrier
	s_add_i32 s27, 0, 0x18000
	s_add_i32 s45, 0, 0x1c000
	v_add_u32_e32 v144, s27, v180
	v_add_u32_e32 v166, s45, v180
	ds_read_b128 v[132:135], v144
	ds_read_b128 v[136:139], v144 offset:1024
	ds_read_b128 v[140:143], v144 offset:2048
	ds_read_b128 v[144:147], v144 offset:3072
	ds_read_b128 v[148:151], v166
	ds_read_b128 v[152:155], v166 offset:1024
	ds_read_b128 v[156:159], v166 offset:2048
	ds_read_b128 v[166:169], v166 offset:3072
	s_add_u32 s24, s24, 0x4000
	s_addc_u32 s25, s25, 0
	s_mov_b32 m0, s41
	v_lshl_add_u64 v[178:179], s[24:25], 0, v[2:3]
	ds_read_b128 v[170:173], v188 offset:32768
	ds_read_b128 v[174:177], v188 offset:33792
	ds_read_b128 v[192:195], v188 offset:34816
	ds_read_b128 v[196:199], v188 offset:35840
	ds_read_b128 v[200:203], v188 offset:36864
	ds_read_b128 v[204:207], v188 offset:37888
	ds_read_b128 v[214:217], v188 offset:38912
	ds_read_b128 v[218:221], v188 offset:39936
	global_load_lds_dwordx4 v[178:179], off
	v_lshl_add_u64 v[178:179], s[24:25], 0, v[160:161]
	s_mov_b32 m0, s46
	s_nop 0
	global_load_lds_dwordx4 v[178:179], off
	s_waitcnt vmcnt(8)
	s_waitcnt lgkmcnt(0)
	s_barrier
	s_setprio 1
	s_waitcnt lgkmcnt(0)
	v_mfma_f32_16x16x32_bf16 v[128:131], v[132:135], v[170:173], v[128:131]
	v_mfma_f32_16x16x32_bf16 v[124:127], v[140:143], v[170:173], v[124:127]
	v_mfma_f32_16x16x32_bf16 v[116:119], v[132:135], v[192:195], v[116:119]
	v_mfma_f32_16x16x32_bf16 v[112:115], v[140:143], v[192:195], v[112:115]
	v_mfma_f32_16x16x32_bf16 v[96:99], v[132:135], v[200:203], v[96:99]
	v_mfma_f32_16x16x32_bf16 v[92:95], v[140:143], v[200:203], v[92:95]
	v_mfma_f32_16x16x32_bf16 v[80:83], v[132:135], v[214:217], v[80:83]
	v_mfma_f32_16x16x32_bf16 v[84:87], v[140:143], v[214:217], v[84:87]
	v_mfma_f32_16x16x32_bf16 v[128:131], v[136:139], v[174:177], v[128:131]
	v_mfma_f32_16x16x32_bf16 v[124:127], v[144:147], v[174:177], v[124:127]
	v_mfma_f32_16x16x32_bf16 v[116:119], v[136:139], v[196:199], v[116:119]
	v_mfma_f32_16x16x32_bf16 v[112:115], v[144:147], v[196:199], v[112:115]
	v_mfma_f32_16x16x32_bf16 v[96:99], v[136:139], v[204:207], v[96:99]
	v_mfma_f32_16x16x32_bf16 v[92:95], v[144:147], v[204:207], v[92:95]
	v_mfma_f32_16x16x32_bf16 v[80:83], v[136:139], v[218:221], v[80:83]
	v_mfma_f32_16x16x32_bf16 v[84:87], v[144:147], v[218:221], v[84:87]
	s_setprio 0
	s_setprio 1
	v_mfma_f32_16x16x32_bf16 v[120:123], v[148:151], v[170:173], v[120:123]
	v_mfma_f32_16x16x32_bf16 v[108:111], v[156:159], v[170:173], v[108:111]
	v_mfma_f32_16x16x32_bf16 v[104:107], v[148:151], v[192:195], v[104:107]
	v_mfma_f32_16x16x32_bf16 v[100:103], v[156:159], v[192:195], v[100:103]
	v_mfma_f32_16x16x32_bf16 v[88:91], v[148:151], v[200:203], v[88:91]
	v_mfma_f32_16x16x32_bf16 v[72:75], v[156:159], v[200:203], v[72:75]
	v_mfma_f32_16x16x32_bf16 v[68:71], v[148:151], v[214:217], v[68:71]
	v_mfma_f32_16x16x32_bf16 v[64:67], v[156:159], v[214:217], v[64:67]
	v_mfma_f32_16x16x32_bf16 v[120:123], v[152:155], v[174:177], v[120:123]
	v_mfma_f32_16x16x32_bf16 v[108:111], v[166:169], v[174:177], v[108:111]
	v_mfma_f32_16x16x32_bf16 v[104:107], v[152:155], v[196:199], v[104:107]
	v_mfma_f32_16x16x32_bf16 v[100:103], v[166:169], v[196:199], v[100:103]
	v_mfma_f32_16x16x32_bf16 v[88:91], v[152:155], v[204:207], v[88:91]
	v_mfma_f32_16x16x32_bf16 v[72:75], v[166:169], v[204:207], v[72:75]
	v_mfma_f32_16x16x32_bf16 v[68:71], v[152:155], v[218:221], v[68:71]
	v_mfma_f32_16x16x32_bf16 v[64:67], v[166:169], v[218:221], v[64:67]
	s_setprio 0
	s_barrier
	s_add_u32 s24, s22, 0x8000
	s_addc_u32 s25, s23, 0
	s_add_i32 s27, s27, s78
	v_lshl_add_u64 v[178:179], s[24:25], 0, v[2:3]
	s_mov_b32 m0, s27
	ds_read_b128 v[170:173], v188 offset:49152
	ds_read_b128 v[174:177], v188 offset:50176
	ds_read_b128 v[192:195], v188 offset:51200
	ds_read_b128 v[196:199], v188 offset:52224
	ds_read_b128 v[200:203], v188 offset:53248
	ds_read_b128 v[204:207], v188 offset:54272
	ds_read_b128 v[214:217], v188 offset:55296
	ds_read_b128 v[218:221], v188 offset:56320
	global_load_lds_dwordx4 v[178:179], off
	s_add_i32 m0, s27, 0x2000
	s_add_u32 s22, s22, 0xc000
	v_lshl_add_u64 v[178:179], s[24:25], 0, v[160:161]
	s_addc_u32 s23, s23, 0
	s_add_i32 s24, s45, s78
	global_load_lds_dwordx4 v[178:179], off
	v_lshl_add_u64 v[178:179], s[22:23], 0, v[2:3]
	s_mov_b32 m0, s24
	s_nop 0
	global_load_lds_dwordx4 v[178:179], off
	v_lshl_add_u64 v[178:179], s[22:23], 0, v[160:161]
	s_add_i32 m0, s24, 0x2000
	s_nop 0
	global_load_lds_dwordx4 v[178:179], off
	v_lshl_add_u64 v[178:179], s[20:21], 0, v[2:3]
	s_mov_b32 m0, s52
	s_nop 0
	global_load_lds_dwordx4 v[178:179], off
	v_lshl_add_u64 v[178:179], s[20:21], 0, v[160:161]
	s_mov_b32 m0, s53
	s_nop 0
	global_load_lds_dwordx4 v[178:179], off
	s_waitcnt vmcnt(8)
	s_waitcnt lgkmcnt(0)
	s_barrier
	s_setprio 1
	s_waitcnt lgkmcnt(0)
	v_mfma_f32_16x16x32_bf16 v[60:63], v[132:135], v[170:173], v[60:63]
	v_mfma_f32_16x16x32_bf16 v[56:59], v[140:143], v[170:173], v[56:59]
	v_mfma_f32_16x16x32_bf16 v[44:47], v[132:135], v[192:195], v[44:47]
	v_mfma_f32_16x16x32_bf16 v[48:51], v[140:143], v[192:195], v[48:51]
	v_mfma_f32_16x16x32_bf16 v[28:31], v[132:135], v[200:203], v[28:31]
	v_mfma_f32_16x16x32_bf16 v[24:27], v[140:143], v[200:203], v[24:27]
	v_mfma_f32_16x16x32_bf16 v[76:79], v[132:135], v[214:217], v[76:79]
	v_mfma_f32_16x16x32_bf16 v[16:19], v[140:143], v[214:217], v[16:19]
	v_mfma_f32_16x16x32_bf16 v[60:63], v[136:139], v[174:177], v[60:63]
	v_mfma_f32_16x16x32_bf16 v[56:59], v[144:147], v[174:177], v[56:59]
	v_mfma_f32_16x16x32_bf16 v[44:47], v[136:139], v[196:199], v[44:47]
	v_mfma_f32_16x16x32_bf16 v[48:51], v[144:147], v[196:199], v[48:51]
	v_mfma_f32_16x16x32_bf16 v[28:31], v[136:139], v[204:207], v[28:31]
	v_mfma_f32_16x16x32_bf16 v[24:27], v[144:147], v[204:207], v[24:27]
	v_mfma_f32_16x16x32_bf16 v[76:79], v[136:139], v[218:221], v[76:79]
	v_mfma_f32_16x16x32_bf16 v[16:19], v[144:147], v[218:221], v[16:19]
	s_setprio 0
	s_setprio 1
	v_mfma_f32_16x16x32_bf16 v[52:55], v[148:151], v[170:173], v[52:55]
	v_mfma_f32_16x16x32_bf16 v[40:43], v[156:159], v[170:173], v[40:43]
	v_mfma_f32_16x16x32_bf16 v[36:39], v[148:151], v[192:195], v[36:39]
	v_mfma_f32_16x16x32_bf16 v[32:35], v[156:159], v[192:195], v[32:35]
	v_mfma_f32_16x16x32_bf16 v[20:23], v[148:151], v[200:203], v[20:23]
	v_mfma_f32_16x16x32_bf16 v[12:15], v[156:159], v[200:203], v[12:15]
	v_mfma_f32_16x16x32_bf16 v[4:7], v[148:151], v[214:217], v[4:7]
	v_mfma_f32_16x16x32_bf16 v[8:11], v[156:159], v[214:217], v[8:11]
	v_mfma_f32_16x16x32_bf16 v[52:55], v[152:155], v[174:177], v[52:55]
	v_mfma_f32_16x16x32_bf16 v[40:43], v[166:169], v[174:177], v[40:43]
	v_mfma_f32_16x16x32_bf16 v[36:39], v[152:155], v[196:199], v[36:39]
	v_mfma_f32_16x16x32_bf16 v[32:35], v[166:169], v[196:199], v[32:35]
	v_mfma_f32_16x16x32_bf16 v[20:23], v[152:155], v[204:207], v[20:23]
	v_mfma_f32_16x16x32_bf16 v[12:15], v[166:169], v[204:207], v[12:15]
	v_mfma_f32_16x16x32_bf16 v[4:7], v[152:155], v[218:221], v[4:7]
	v_mfma_f32_16x16x32_bf16 v[8:11], v[166:169], v[218:221], v[8:11]
	s_setprio 0
	s_barrier
	s_add_i32 s26, s26, 2
	s_add_u32 s18, s18, 0x10000
	s_addc_u32 s19, s19, 0
	s_add_u32 s6, s6, 0x10000
	s_addc_u32 s7, s7, 0
	s_cmpk_gt_u32 s26, 0x55
